# row phases: the once-per-wave gain folds (G*GA, (1+sc)*GB) moved into the shadow of the first row's cold load
# speedup vs baseline: 1.0046x; 1.0046x over previous
.LBB0_49:
	s_add_i32 s0, s76, -2
	s_mul_hi_i32 s1, s0, 0x38e38e39
	s_lshr_b32 s4, s1, 31
	s_ashr_i32 s1, s1, 1
	s_add_i32 s6, s1, s4
	s_mul_i32 s1, s6, 9
	s_mov_b32 s4, s6
	s_sub_i32 s20, s0, s1
	v_writelane_b32 v254, s4, 34
	s_add_u32 s0, s84, 0xaeca000
	s_addc_u32 s1, s85, 0
	v_writelane_b32 v254, s5, 35
	v_writelane_b32 v254, s0, 36
	v_readfirstlane_b32 s28, v160
	s_nop 0
	v_writelane_b32 v254, s1, 37
	s_nop 0
	v_readlane_b32 s0, v254, 32
	v_readlane_b32 s1, v254, 33
	v_readlane_b32 s4, v254, 14
	s_lshl_b64 s[0:1], s[0:1], 2
	v_readlane_b32 s18, v254, 28
	v_readlane_b32 s5, v254, 15
	v_readlane_b32 s19, v254, 29
	s_add_u32 s4, s18, s0
	s_addc_u32 s5, s19, s1
	v_readlane_b32 s6, v254, 16
	v_readlane_b32 s7, v254, 17
	v_readlane_b32 s8, v254, 18
	v_readlane_b32 s9, v254, 19
	v_readlane_b32 s10, v254, 20
	v_readlane_b32 s11, v254, 21
	v_readlane_b32 s12, v254, 22
	v_readlane_b32 s13, v254, 23
	v_readlane_b32 s14, v254, 24
	v_readlane_b32 s15, v254, 25
	v_readlane_b32 s16, v254, 26
	v_readlane_b32 s17, v254, 27
	v_writelane_b32 v254, s4, 38
	s_cmp_lt_i32 s20, 4
	s_nop 0
	v_writelane_b32 v254, s5, 39
	v_writelane_b32 v254, s20, 40
	s_mov_b64 s[4:5], -1
	s_cbranch_scc1 .LBB0_214
	v_readlane_b32 s4, v254, 40
	s_cmp_lt_i32 s4, 6
	s_mov_b64 s[4:5], -1
	s_cbranch_scc1 .LBB0_168
	v_readlane_b32 s4, v254, 40
	s_cmp_lt_i32 s4, 7
	s_mov_b64 s[4:5], -1
	s_cbranch_scc1 .LBB0_150
	v_readlane_b32 s4, v254, 40
	s_cmp_lt_i32 s4, 8
	s_mov_b64 s[4:5], -1
	s_cbranch_scc1 .LBB0_101
	v_readlane_b32 s4, v254, 40
	s_cmp_eq_u32 s4, 8
	s_cbranch_scc0 .LBB0_100
	s_cmp_eq_u32 s76, 37
	s_cbranch_scc1 .Lrow2_last
	v_readfirstlane_b32 s0, v160
	v_readlane_b32 s1, v252, 7
	s_lshr_b32 s0, s0, 6
	s_mov_b32 s73, s0
	s_add_i32 s0, s0, s1
	v_readlane_b32 s62, v254, 34
	s_sub_u32 s64, s78, 0x110
	s_subb_u32 s65, s79, 0
	s_load_dwordx2 s[66:67], s[64:65], 0x40
	s_load_dwordx2 s[10:11], s[64:65], 0xf8
	s_lshl_b32 s63, s0, 11
	s_add_u32 s4, s84, 0x167ca000
	s_addc_u32 s5, s85, 0
	s_add_u32 s4, s4, s63
	s_addc_u32 s5, s5, 0
	s_add_u32 s6, s84, 0x112ca000
	s_addc_u32 s7, s85, 0
	s_add_u32 s6, s6, s63
	s_addc_u32 s7, s7, 0
	v_and_b32_e32 v0, 63, v160
	v_lshlrev_b32_e32 v1, 4, v0
	v_lshlrev_b32_e32 v0, 3, v0
	v_add_u32_e32 v2, 0x400000, v0
	v_add_u32_e32 v3, 0x800000, v0
	v_add_u32_e32 v4, 0xc00000, v0
	v_add_u32_e32 v5, 0x1000000, v0
	global_load_dwordx2 v[8:9], v5, s[6:7] offset:0 nt
	global_load_dwordx2 v[10:11], v5, s[6:7] offset:512 nt
	global_load_dwordx2 v[12:13], v5, s[6:7] offset:1024 nt
	global_load_dwordx2 v[14:15], v5, s[6:7] offset:1536 nt
	global_load_dwordx2 v[16:17], v5, s[4:5] offset:0 nt
	global_load_dwordx2 v[18:19], v5, s[4:5] offset:512 nt
	global_load_dwordx2 v[20:21], v5, s[4:5] offset:1024 nt
	global_load_dwordx2 v[22:23], v5, s[4:5] offset:1536 nt
	s_add_u32 s8, s84, 0xaeca000
	s_addc_u32 s9, s85, 0
	s_add_u32 s8, s8, s63
	s_addc_u32 s9, s9, 0
	s_lshr_b32 s69, s0, 10
	s_add_i32 s69, s69, 1
	s_mul_i32 s69, s69, 0x6000
	s_mul_i32 s68, s62, 0x12000
	s_add_i32 s70, s62, 1
	s_mul_i32 s71, s70, 0x12000
	s_lshl_b32 s70, s70, 14
	s_lshl_b32 s72, s62, 14
	s_add_i32 s72, s72, 0x3000
	s_add_u32 s16, s84, 0x6605000
	s_addc_u32 s17, s85, 0
	s_add_u32 s16, s16, s68
	s_addc_u32 s17, s17, 0
	s_add_u32 s20, s84, 0x6600000
	s_addc_u32 s21, s85, 0
	s_add_u32 s20, s20, s71
	s_addc_u32 s21, s21, 0
	s_add_u32 s18, s20, 0x1000
	s_addc_u32 s19, s21, 0
	s_add_u32 s22, s16, s69
	s_addc_u32 s23, s17, 0
	s_add_u32 s60, s20, s69
	s_addc_u32 s61, s21, 0
	s_add_u32 s26, s18, s69
	s_addc_u32 s27, s19, 0
	s_lshl_b32 s63, s63, 1
	s_waitcnt lgkmcnt(0)
	s_add_u32 s12, s66, s72
	s_addc_u32 s13, s67, 0
	s_add_u32 s14, s66, s70
	s_addc_u32 s15, s67, 0
	s_add_u32 s10, s10, s63
	s_addc_u32 s11, s11, 0
	s_mov_b64 s[74:75], s[12:13]
	s_cmp_eq_u32 s73, 1
	s_cselect_b32 s74, s14, s74
	s_cselect_b32 s75, s15, s75
	s_cmp_eq_u32 s73, 2
	s_cselect_b32 s74, s16, s74
	s_cselect_b32 s75, s17, s75
	s_cmp_eq_u32 s73, 3
	s_cselect_b32 s74, s18, s74
	s_cselect_b32 s75, s19, s75
	s_cmp_eq_u32 s73, 4
	s_cselect_b32 s74, s20, s74
	s_cselect_b32 s75, s21, s75
	s_cmp_eq_u32 s73, 5
	s_cselect_b32 s74, s22, s74
	s_cselect_b32 s75, s23, s75
	s_cmp_eq_u32 s73, 6
	s_cselect_b32 s74, s26, s74
	s_cselect_b32 s75, s27, s75
	s_cmp_eq_u32 s73, 7
	s_cselect_b32 s74, s60, s74
	s_cselect_b32 s75, s61, s75
	global_load_dwordx4 v[222:225], v1, s[74:75] offset:0
	global_load_dwordx4 v[226:229], v1, s[74:75] offset:1024
	global_load_dwordx4 v[230:233], v1, s[74:75] offset:2048
	global_load_dwordx4 v[234:237], v1, s[74:75] offset:3072
	s_lshl_b32 s74, s73, 12
	v_add_u32_e32 v6, s74, v1
	global_load_dwordx2 v[24:25], v0, s[6:7] offset:0 nt
	global_load_dwordx2 v[26:27], v0, s[6:7] offset:512 nt
	global_load_dwordx2 v[28:29], v0, s[6:7] offset:1024 nt
	global_load_dwordx2 v[30:31], v0, s[6:7] offset:1536 nt
	global_load_dwordx2 v[32:33], v0, s[4:5] offset:0 nt
	global_load_dwordx2 v[34:35], v0, s[4:5] offset:512 nt
	global_load_dwordx2 v[36:37], v0, s[4:5] offset:1024 nt
	global_load_dwordx2 v[38:39], v0, s[4:5] offset:1536 nt
	global_load_dwordx2 v[40:41], v2, s[6:7] offset:0 nt
	global_load_dwordx2 v[42:43], v2, s[6:7] offset:512 nt
	global_load_dwordx2 v[44:45], v2, s[6:7] offset:1024 nt
	global_load_dwordx2 v[46:47], v2, s[6:7] offset:1536 nt
	global_load_dwordx2 v[48:49], v2, s[4:5] offset:0 nt
	global_load_dwordx2 v[50:51], v2, s[4:5] offset:512 nt
	global_load_dwordx2 v[52:53], v2, s[4:5] offset:1024 nt
	global_load_dwordx2 v[54:55], v2, s[4:5] offset:1536 nt
	s_waitcnt vmcnt(16)
	ds_write_b128 v6, v[222:225] offset:0
	ds_write_b128 v6, v[226:229] offset:1024
	ds_write_b128 v6, v[230:233] offset:2048
	ds_write_b128 v6, v[234:237] offset:3072
	s_waitcnt lgkmcnt(0)
	s_barrier
	ds_read_b128 v[56:59], v1 offset:0
	ds_read_b128 v[60:63], v1 offset:1024
	ds_read_b128 v[64:67], v1 offset:2048
	ds_read_b128 v[68:71], v1 offset:3072
	ds_read_b128 v[72:75], v1 offset:4096
	ds_read_b128 v[76:79], v1 offset:5120
	ds_read_b128 v[80:83], v1 offset:6144
	ds_read_b128 v[84:87], v1 offset:7168
	ds_read_b128 v[88:91], v1 offset:8192
	ds_read_b128 v[92:95], v1 offset:9216
	ds_read_b128 v[96:99], v1 offset:10240
	ds_read_b128 v[100:103], v1 offset:11264
	ds_read_b128 v[104:107], v1 offset:12288
	ds_read_b128 v[108:111], v1 offset:13312
	ds_read_b128 v[112:115], v1 offset:14336
	ds_read_b128 v[116:119], v1 offset:15360
	ds_read_b128 v[134:137], v1 offset:16384
	ds_read_b128 v[138:141], v1 offset:17408
	ds_read_b128 v[142:145], v1 offset:18432
	ds_read_b128 v[146:149], v1 offset:19456
	ds_read_b128 v[190:193], v1 offset:20480
	ds_read_b128 v[194:197], v1 offset:21504
	ds_read_b128 v[198:201], v1 offset:22528
	ds_read_b128 v[202:205], v1 offset:23552
	ds_read_b128 v[206:209], v1 offset:24576
	ds_read_b128 v[210:213], v1 offset:25600
	ds_read_b128 v[214:217], v1 offset:26624
	ds_read_b128 v[218:221], v1 offset:27648
	ds_read_b128 v[222:225], v1 offset:28672
	ds_read_b128 v[226:229], v1 offset:29696
	ds_read_b128 v[230:233], v1 offset:30720
	ds_read_b128 v[234:237], v1 offset:31744
	s_waitcnt lgkmcnt(0)
	v_mul_f32_e32 v190, v190, v56
	v_mul_f32_e32 v191, v191, v57
	v_mul_f32_e32 v192, v192, v58
	v_mul_f32_e32 v193, v193, v59
	v_mul_f32_e32 v194, v194, v60
	v_mul_f32_e32 v195, v195, v61
	v_mul_f32_e32 v196, v196, v62
	v_mul_f32_e32 v197, v197, v63
	v_mul_f32_e32 v198, v198, v64
	v_mul_f32_e32 v199, v199, v65
	v_mul_f32_e32 v200, v200, v66
	v_mul_f32_e32 v201, v201, v67
	v_mul_f32_e32 v202, v202, v68
	v_mul_f32_e32 v203, v203, v69
	v_mul_f32_e32 v204, v204, v70
	v_mul_f32_e32 v205, v205, v71
	v_mul_f32_e32 v88, v88, v56
	v_mul_f32_e32 v89, v89, v57
	v_mul_f32_e32 v90, v90, v58
	v_mul_f32_e32 v91, v91, v59
	v_mul_f32_e32 v92, v92, v60
	v_mul_f32_e32 v93, v93, v61
	v_mul_f32_e32 v94, v94, v62
	v_mul_f32_e32 v95, v95, v63
	v_mul_f32_e32 v96, v96, v64
	v_mul_f32_e32 v97, v97, v65
	v_mul_f32_e32 v98, v98, v66
	v_mul_f32_e32 v99, v99, v67
	v_mul_f32_e32 v100, v100, v68
	v_mul_f32_e32 v101, v101, v69
	v_mul_f32_e32 v102, v102, v70
	v_mul_f32_e32 v103, v103, v71
	v_add_f32_e32 v206, 1.0, v206
	v_add_f32_e32 v207, 1.0, v207
	v_add_f32_e32 v208, 1.0, v208
	v_add_f32_e32 v209, 1.0, v209
	v_add_f32_e32 v210, 1.0, v210
	v_add_f32_e32 v211, 1.0, v211
	v_add_f32_e32 v212, 1.0, v212
	v_add_f32_e32 v213, 1.0, v213
	v_add_f32_e32 v214, 1.0, v214
	v_add_f32_e32 v215, 1.0, v215
	v_add_f32_e32 v216, 1.0, v216
	v_add_f32_e32 v217, 1.0, v217
	v_add_f32_e32 v218, 1.0, v218
	v_add_f32_e32 v219, 1.0, v219
	v_add_f32_e32 v220, 1.0, v220
	v_add_f32_e32 v221, 1.0, v221
	v_mul_f32_e32 v206, v206, v72
	v_mul_f32_e32 v207, v207, v73
	v_mul_f32_e32 v208, v208, v74
	v_mul_f32_e32 v209, v209, v75
	v_mul_f32_e32 v210, v210, v76
	v_mul_f32_e32 v211, v211, v77
	v_mul_f32_e32 v212, v212, v78
	v_mul_f32_e32 v213, v213, v79
	v_mul_f32_e32 v214, v214, v80
	v_mul_f32_e32 v215, v215, v81
	v_mul_f32_e32 v216, v216, v82
	v_mul_f32_e32 v217, v217, v83
	v_mul_f32_e32 v218, v218, v84
	v_mul_f32_e32 v219, v219, v85
	v_mul_f32_e32 v220, v220, v86
	v_mul_f32_e32 v221, v221, v87
	v_add_f32_e32 v104, 1.0, v104
	v_add_f32_e32 v105, 1.0, v105
	v_add_f32_e32 v106, 1.0, v106
	v_add_f32_e32 v107, 1.0, v107
	v_add_f32_e32 v108, 1.0, v108
	v_add_f32_e32 v109, 1.0, v109
	v_add_f32_e32 v110, 1.0, v110
	v_add_f32_e32 v111, 1.0, v111
	v_add_f32_e32 v112, 1.0, v112
	v_add_f32_e32 v113, 1.0, v113
	v_add_f32_e32 v114, 1.0, v114
	v_add_f32_e32 v115, 1.0, v115
	v_add_f32_e32 v116, 1.0, v116
	v_add_f32_e32 v117, 1.0, v117
	v_add_f32_e32 v118, 1.0, v118
	v_add_f32_e32 v119, 1.0, v119
	v_mul_f32_e32 v104, v104, v72
	v_mul_f32_e32 v105, v105, v73
	v_mul_f32_e32 v106, v106, v74
	v_mul_f32_e32 v107, v107, v75
	v_mul_f32_e32 v108, v108, v76
	v_mul_f32_e32 v109, v109, v77
	v_mul_f32_e32 v110, v110, v78
	v_mul_f32_e32 v111, v111, v79
	v_mul_f32_e32 v112, v112, v80
	v_mul_f32_e32 v113, v113, v81
	v_mul_f32_e32 v114, v114, v82
	v_mul_f32_e32 v115, v115, v83
	v_mul_f32_e32 v116, v116, v84
	v_mul_f32_e32 v117, v117, v85
	v_mul_f32_e32 v118, v118, v86
	v_mul_f32_e32 v119, v119, v87
	v_lshlrev_b32_e32 v246, 16, v8
	v_and_b32_e32 v8, 0xffff0000, v8
	v_lshlrev_b32_e32 v247, 16, v9
	v_and_b32_e32 v9, 0xffff0000, v9
	v_lshlrev_b32_e32 v248, 16, v10
	v_and_b32_e32 v10, 0xffff0000, v10
	v_lshlrev_b32_e32 v249, 16, v11
	v_and_b32_e32 v11, 0xffff0000, v11
	v_lshlrev_b32_e32 v250, 16, v12
	v_and_b32_e32 v12, 0xffff0000, v12
	v_lshlrev_b32_e32 v251, 16, v13
	v_and_b32_e32 v13, 0xffff0000, v13
	v_lshlrev_b32_e32 v176, 16, v14
	v_and_b32_e32 v14, 0xffff0000, v14
	v_lshlrev_b32_e32 v177, 16, v15
	v_and_b32_e32 v15, 0xffff0000, v15
	v_mul_f32_e32 v178, v246, v246
	v_fmac_f32_e32 v178, v8, v8
	v_fmac_f32_e32 v178, v247, v247
	v_fmac_f32_e32 v178, v9, v9
	v_fmac_f32_e32 v178, v248, v248
	v_fmac_f32_e32 v178, v10, v10
	v_fmac_f32_e32 v178, v249, v249
	v_fmac_f32_e32 v178, v11, v11
	v_fmac_f32_e32 v178, v250, v250
	v_fmac_f32_e32 v178, v12, v12
	v_fmac_f32_e32 v178, v251, v251
	v_fmac_f32_e32 v178, v13, v13
	v_fmac_f32_e32 v178, v176, v176
	v_fmac_f32_e32 v178, v14, v14
	v_fmac_f32_e32 v178, v177, v177
	v_fmac_f32_e32 v178, v15, v15
	v_lshlrev_b32_e32 v238, 16, v16
	v_and_b32_e32 v16, 0xffff0000, v16
	v_add_f32_dpp v178, v178, v178 quad_perm:[1,0,3,2] row_mask:0xf bank_mask:0xf bound_ctrl:1
	v_lshlrev_b32_e32 v239, 16, v17
	v_and_b32_e32 v17, 0xffff0000, v17
	v_add_f32_dpp v178, v178, v178 quad_perm:[2,3,0,1] row_mask:0xf bank_mask:0xf bound_ctrl:1
	v_lshlrev_b32_e32 v240, 16, v18
	v_and_b32_e32 v18, 0xffff0000, v18
	v_add_f32_dpp v178, v178, v178 row_half_mirror row_mask:0xf bank_mask:0xf bound_ctrl:1
	v_lshlrev_b32_e32 v241, 16, v19
	v_and_b32_e32 v19, 0xffff0000, v19
	v_add_f32_dpp v178, v178, v178 row_mirror row_mask:0xf bank_mask:0xf bound_ctrl:1
	v_lshlrev_b32_e32 v242, 16, v20
	v_and_b32_e32 v20, 0xffff0000, v20
	v_add_f32_dpp v178, v178, v178 row_bcast:15 row_mask:0xa bank_mask:0xf
	v_lshlrev_b32_e32 v243, 16, v21
	v_and_b32_e32 v21, 0xffff0000, v21
	v_add_f32_dpp v178, v178, v178 row_bcast:31 row_mask:0xc bank_mask:0xf
	v_lshlrev_b32_e32 v244, 16, v22
	v_and_b32_e32 v22, 0xffff0000, v22
	v_lshlrev_b32_e32 v245, 16, v23
	v_and_b32_e32 v23, 0xffff0000, v23
	v_readlane_b32 s0, v178, 63
	s_nop 1
	v_mov_b32_e32 v181, s0
	v_fmamk_f32 v181, v181, 0x3a800000, v161
	v_rsq_f32_e32 v179, v181
	s_nop 0
	s_waitcnt lgkmcnt(0)
	v_mul_f32_e32 v246, v246, v179
	v_mul_f32_e32 v8, v8, v179
	v_mul_f32_e32 v247, v247, v179
	v_mul_f32_e32 v9, v9, v179
	v_mul_f32_e32 v248, v248, v179
	v_mul_f32_e32 v10, v10, v179
	v_mul_f32_e32 v249, v249, v179
	v_mul_f32_e32 v11, v11, v179
	v_mul_f32_e32 v250, v250, v179
	v_mul_f32_e32 v12, v12, v179
	v_mul_f32_e32 v251, v251, v179
	v_mul_f32_e32 v13, v13, v179
	v_mul_f32_e32 v176, v176, v179
	v_mul_f32_e32 v14, v14, v179
	v_mul_f32_e32 v177, v177, v179
	v_mul_f32_e32 v15, v15, v179
	v_fmac_f32_e32 v238, v190, v246
	v_fmac_f32_e32 v16, v191, v8
	v_fmac_f32_e32 v239, v192, v247
	v_fmac_f32_e32 v17, v193, v9
	v_fmac_f32_e32 v240, v194, v248
	v_fmac_f32_e32 v18, v195, v10
	v_fmac_f32_e32 v241, v196, v249
	v_fmac_f32_e32 v19, v197, v11
	v_fmac_f32_e32 v242, v198, v250
	v_fmac_f32_e32 v20, v199, v12
	v_fmac_f32_e32 v243, v200, v251
	v_fmac_f32_e32 v21, v201, v13
	v_fmac_f32_e32 v244, v202, v176
	v_fmac_f32_e32 v22, v203, v14
	v_fmac_f32_e32 v245, v204, v177
	v_fmac_f32_e32 v23, v205, v15
	v_cvt_pk_bf16_f32 v120, v238, v16
	v_cvt_pk_bf16_f32 v121, v239, v17
	global_store_dwordx2 v5, v[120:121], s[4:5] offset:0 nt
	v_cvt_pk_bf16_f32 v122, v240, v18
	v_cvt_pk_bf16_f32 v123, v241, v19
	global_store_dwordx2 v5, v[122:123], s[4:5] offset:512 nt
	v_cvt_pk_bf16_f32 v124, v242, v20
	v_cvt_pk_bf16_f32 v125, v243, v21
	global_store_dwordx2 v5, v[124:125], s[4:5] offset:1024 nt
	v_cvt_pk_bf16_f32 v126, v244, v22
	v_cvt_pk_bf16_f32 v127, v245, v23
	global_store_dwordx2 v5, v[126:127], s[4:5] offset:1536 nt
	v_mul_f32_e32 v178, v238, v238
	v_fmac_f32_e32 v178, v16, v16
	v_fmac_f32_e32 v178, v239, v239
	v_fmac_f32_e32 v178, v17, v17
	v_fmac_f32_e32 v178, v240, v240
	v_fmac_f32_e32 v178, v18, v18
	v_fmac_f32_e32 v178, v241, v241
	v_fmac_f32_e32 v178, v19, v19
	v_fmac_f32_e32 v178, v242, v242
	v_fmac_f32_e32 v178, v20, v20
	v_fmac_f32_e32 v178, v243, v243
	v_fmac_f32_e32 v178, v21, v21
	v_fmac_f32_e32 v178, v244, v244
	v_fmac_f32_e32 v178, v22, v22
	v_fmac_f32_e32 v178, v245, v245
	v_fmac_f32_e32 v178, v23, v23
	s_nop 1
	v_add_f32_dpp v178, v178, v178 quad_perm:[1,0,3,2] row_mask:0xf bank_mask:0xf bound_ctrl:1
	s_nop 1
	v_add_f32_dpp v178, v178, v178 quad_perm:[2,3,0,1] row_mask:0xf bank_mask:0xf bound_ctrl:1
	s_nop 1
	v_add_f32_dpp v178, v178, v178 row_half_mirror row_mask:0xf bank_mask:0xf bound_ctrl:1
	s_nop 1
	v_add_f32_dpp v178, v178, v178 row_mirror row_mask:0xf bank_mask:0xf bound_ctrl:1
	s_nop 1
	v_add_f32_dpp v178, v178, v178 row_bcast:15 row_mask:0xa bank_mask:0xf
	s_nop 1
	v_add_f32_dpp v178, v178, v178 row_bcast:31 row_mask:0xc bank_mask:0xf
	s_nop 0
	v_readlane_b32 s0, v178, 63
	s_nop 1
	v_mov_b32_e32 v181, s0
	v_fmamk_f32 v181, v181, 0x3a800000, v161
	v_rsq_f32_e32 v180, v181
	s_nop 0
	v_mul_f32_e32 v238, v238, v180
	v_mul_f32_e32 v16, v16, v180
	v_mul_f32_e32 v239, v239, v180
	v_mul_f32_e32 v17, v17, v180
	v_mul_f32_e32 v240, v240, v180
	v_mul_f32_e32 v18, v18, v180
	v_mul_f32_e32 v241, v241, v180
	v_mul_f32_e32 v19, v19, v180
	v_mul_f32_e32 v242, v242, v180
	v_mul_f32_e32 v20, v20, v180
	v_mul_f32_e32 v243, v243, v180
	v_mul_f32_e32 v21, v21, v180
	v_mul_f32_e32 v244, v244, v180
	v_mul_f32_e32 v22, v22, v180
	v_mul_f32_e32 v245, v245, v180
	v_mul_f32_e32 v23, v23, v180
	v_fma_f32 v238, v238, v206, v222
	v_fma_f32 v16, v16, v207, v223
	v_fma_f32 v239, v239, v208, v224
	v_fma_f32 v17, v17, v209, v225
	v_fma_f32 v240, v240, v210, v226
	v_fma_f32 v18, v18, v211, v227
	v_fma_f32 v241, v241, v212, v228
	v_fma_f32 v19, v19, v213, v229
	v_fma_f32 v242, v242, v214, v230
	v_fma_f32 v20, v20, v215, v231
	v_fma_f32 v243, v243, v216, v232
	v_fma_f32 v21, v21, v217, v233
	v_fma_f32 v244, v244, v218, v234
	v_fma_f32 v22, v22, v219, v235
	v_fma_f32 v245, v245, v220, v236
	v_fma_f32 v23, v23, v221, v237
	v_cvt_pk_bf16_f32 v150, v238, v16
	v_cvt_pk_bf16_f32 v151, v239, v17
	global_store_dwordx2 v5, v[150:151], s[8:9] offset:0
	v_cvt_pk_bf16_f32 v152, v240, v18
	v_cvt_pk_bf16_f32 v153, v241, v19
	global_store_dwordx2 v5, v[152:153], s[8:9] offset:512
	v_cvt_pk_bf16_f32 v154, v242, v20
	v_cvt_pk_bf16_f32 v155, v243, v21
	global_store_dwordx2 v5, v[154:155], s[8:9] offset:1024
	v_cvt_pk_bf16_f32 v156, v244, v22
	v_cvt_pk_bf16_f32 v157, v245, v23
	global_store_dwordx2 v5, v[156:157], s[8:9] offset:1536
	global_load_dwordx2 v[8:9], v3, s[6:7] offset:0 nt
	global_load_dwordx2 v[10:11], v3, s[6:7] offset:512 nt
	global_load_dwordx2 v[12:13], v3, s[6:7] offset:1024 nt
	global_load_dwordx2 v[14:15], v3, s[6:7] offset:1536 nt
	global_load_dwordx2 v[16:17], v3, s[4:5] offset:0 nt
	global_load_dwordx2 v[18:19], v3, s[4:5] offset:512 nt
	global_load_dwordx2 v[20:21], v3, s[4:5] offset:1024 nt
	global_load_dwordx2 v[22:23], v3, s[4:5] offset:1536 nt
	global_load_dwordx2 v[190:191], v4, s[6:7] offset:0 nt
	global_load_dwordx2 v[192:193], v4, s[6:7] offset:512 nt
	global_load_dwordx2 v[194:195], v4, s[6:7] offset:1024 nt
	global_load_dwordx2 v[196:197], v4, s[6:7] offset:1536 nt
	global_load_dwordx2 v[198:199], v4, s[4:5] offset:0 nt
	global_load_dwordx2 v[200:201], v4, s[4:5] offset:512 nt
	global_load_dwordx2 v[202:203], v4, s[4:5] offset:1024 nt
	global_load_dwordx2 v[204:205], v4, s[4:5] offset:1536 nt
	s_waitcnt vmcnt(36)
	v_lshlrev_b32_e32 v246, 16, v24
	v_and_b32_e32 v24, 0xffff0000, v24
	v_lshlrev_b32_e32 v247, 16, v25
	v_and_b32_e32 v25, 0xffff0000, v25
	v_lshlrev_b32_e32 v248, 16, v26
	v_and_b32_e32 v26, 0xffff0000, v26
	v_lshlrev_b32_e32 v249, 16, v27
	v_and_b32_e32 v27, 0xffff0000, v27
	v_lshlrev_b32_e32 v250, 16, v28
	v_and_b32_e32 v28, 0xffff0000, v28
	v_lshlrev_b32_e32 v251, 16, v29
	v_and_b32_e32 v29, 0xffff0000, v29
	v_lshlrev_b32_e32 v176, 16, v30
	v_and_b32_e32 v30, 0xffff0000, v30
	v_lshlrev_b32_e32 v177, 16, v31
	v_and_b32_e32 v31, 0xffff0000, v31
	v_mul_f32_e32 v178, v246, v246
	v_fmac_f32_e32 v178, v24, v24
	v_fmac_f32_e32 v178, v247, v247
	v_fmac_f32_e32 v178, v25, v25
	v_fmac_f32_e32 v178, v248, v248
	v_fmac_f32_e32 v178, v26, v26
	v_fmac_f32_e32 v178, v249, v249
	v_fmac_f32_e32 v178, v27, v27
	v_fmac_f32_e32 v178, v250, v250
	v_fmac_f32_e32 v178, v28, v28
	v_fmac_f32_e32 v178, v251, v251
	v_fmac_f32_e32 v178, v29, v29
	v_fmac_f32_e32 v178, v176, v176
	v_fmac_f32_e32 v178, v30, v30
	v_fmac_f32_e32 v178, v177, v177
	v_fmac_f32_e32 v178, v31, v31
	s_waitcnt vmcnt(32)
	v_lshlrev_b32_e32 v238, 16, v32
	v_and_b32_e32 v32, 0xffff0000, v32
	v_add_f32_dpp v178, v178, v178 quad_perm:[1,0,3,2] row_mask:0xf bank_mask:0xf bound_ctrl:1
	v_lshlrev_b32_e32 v239, 16, v33
	v_and_b32_e32 v33, 0xffff0000, v33
	v_add_f32_dpp v178, v178, v178 quad_perm:[2,3,0,1] row_mask:0xf bank_mask:0xf bound_ctrl:1
	v_lshlrev_b32_e32 v240, 16, v34
	v_and_b32_e32 v34, 0xffff0000, v34
	v_add_f32_dpp v178, v178, v178 row_half_mirror row_mask:0xf bank_mask:0xf bound_ctrl:1
	v_lshlrev_b32_e32 v241, 16, v35
	v_and_b32_e32 v35, 0xffff0000, v35
	v_add_f32_dpp v178, v178, v178 row_mirror row_mask:0xf bank_mask:0xf bound_ctrl:1
	v_lshlrev_b32_e32 v242, 16, v36
	v_and_b32_e32 v36, 0xffff0000, v36
	v_add_f32_dpp v178, v178, v178 row_bcast:15 row_mask:0xa bank_mask:0xf
	v_lshlrev_b32_e32 v243, 16, v37
	v_and_b32_e32 v37, 0xffff0000, v37
	v_add_f32_dpp v178, v178, v178 row_bcast:31 row_mask:0xc bank_mask:0xf
	v_lshlrev_b32_e32 v244, 16, v38
	v_and_b32_e32 v38, 0xffff0000, v38
	v_lshlrev_b32_e32 v245, 16, v39
	v_and_b32_e32 v39, 0xffff0000, v39
	v_readlane_b32 s0, v178, 63
	s_nop 1
	v_mov_b32_e32 v181, s0
	v_fmamk_f32 v181, v181, 0x3a800000, v161
	v_rsq_f32_e32 v179, v181
	s_nop 0
	v_mul_f32_e32 v246, v246, v179
	v_mul_f32_e32 v24, v24, v179
	v_mul_f32_e32 v247, v247, v179
	v_mul_f32_e32 v25, v25, v179
	v_mul_f32_e32 v248, v248, v179
	v_mul_f32_e32 v26, v26, v179
	v_mul_f32_e32 v249, v249, v179
	v_mul_f32_e32 v27, v27, v179
	v_mul_f32_e32 v250, v250, v179
	v_mul_f32_e32 v28, v28, v179
	v_mul_f32_e32 v251, v251, v179
	v_mul_f32_e32 v29, v29, v179
	v_mul_f32_e32 v176, v176, v179
	v_mul_f32_e32 v30, v30, v179
	v_mul_f32_e32 v177, v177, v179
	v_mul_f32_e32 v31, v31, v179
	v_fmac_f32_e32 v238, v88, v246
	v_fmac_f32_e32 v32, v89, v24
	v_fmac_f32_e32 v239, v90, v247
	v_fmac_f32_e32 v33, v91, v25
	v_fmac_f32_e32 v240, v92, v248
	v_fmac_f32_e32 v34, v93, v26
	v_fmac_f32_e32 v241, v94, v249
	v_fmac_f32_e32 v35, v95, v27
	v_fmac_f32_e32 v242, v96, v250
	v_fmac_f32_e32 v36, v97, v28
	v_fmac_f32_e32 v243, v98, v251
	v_fmac_f32_e32 v37, v99, v29
	v_fmac_f32_e32 v244, v100, v176
	v_fmac_f32_e32 v38, v101, v30
	v_fmac_f32_e32 v245, v102, v177
	v_fmac_f32_e32 v39, v103, v31
	v_cvt_pk_bf16_f32 v120, v238, v32
	v_cvt_pk_bf16_f32 v121, v239, v33
	global_store_dwordx2 v0, v[120:121], s[4:5] offset:0 nt
	v_cvt_pk_bf16_f32 v122, v240, v34
	v_cvt_pk_bf16_f32 v123, v241, v35
	global_store_dwordx2 v0, v[122:123], s[4:5] offset:512 nt
	v_cvt_pk_bf16_f32 v124, v242, v36
	v_cvt_pk_bf16_f32 v125, v243, v37
	global_store_dwordx2 v0, v[124:125], s[4:5] offset:1024 nt
	v_cvt_pk_bf16_f32 v126, v244, v38
	v_cvt_pk_bf16_f32 v127, v245, v39
	global_store_dwordx2 v0, v[126:127], s[4:5] offset:1536 nt
	v_mul_f32_e32 v178, v238, v238
	v_fmac_f32_e32 v178, v32, v32
	v_fmac_f32_e32 v178, v239, v239
	v_fmac_f32_e32 v178, v33, v33
	v_fmac_f32_e32 v178, v240, v240
	v_fmac_f32_e32 v178, v34, v34
	v_fmac_f32_e32 v178, v241, v241
	v_fmac_f32_e32 v178, v35, v35
	v_fmac_f32_e32 v178, v242, v242
	v_fmac_f32_e32 v178, v36, v36
	v_fmac_f32_e32 v178, v243, v243
	v_fmac_f32_e32 v178, v37, v37
	v_fmac_f32_e32 v178, v244, v244
	v_fmac_f32_e32 v178, v38, v38
	v_fmac_f32_e32 v178, v245, v245
	v_fmac_f32_e32 v178, v39, v39
	s_nop 1
	v_add_f32_dpp v178, v178, v178 quad_perm:[1,0,3,2] row_mask:0xf bank_mask:0xf bound_ctrl:1
	s_nop 1
	v_add_f32_dpp v178, v178, v178 quad_perm:[2,3,0,1] row_mask:0xf bank_mask:0xf bound_ctrl:1
	s_nop 1
	v_add_f32_dpp v178, v178, v178 row_half_mirror row_mask:0xf bank_mask:0xf bound_ctrl:1
	s_nop 1
	v_add_f32_dpp v178, v178, v178 row_mirror row_mask:0xf bank_mask:0xf bound_ctrl:1
	s_nop 1
	v_add_f32_dpp v178, v178, v178 row_bcast:15 row_mask:0xa bank_mask:0xf
	s_nop 1
	v_add_f32_dpp v178, v178, v178 row_bcast:31 row_mask:0xc bank_mask:0xf
	s_nop 0
	v_readlane_b32 s0, v178, 63
	s_nop 1
	v_mov_b32_e32 v181, s0
	v_fmamk_f32 v181, v181, 0x3a800000, v161
	v_rsq_f32_e32 v180, v181
	s_nop 0
	v_mul_f32_e32 v238, v238, v180
	v_mul_f32_e32 v32, v32, v180
	v_mul_f32_e32 v239, v239, v180
	v_mul_f32_e32 v33, v33, v180
	v_mul_f32_e32 v240, v240, v180
	v_mul_f32_e32 v34, v34, v180
	v_mul_f32_e32 v241, v241, v180
	v_mul_f32_e32 v35, v35, v180
	v_mul_f32_e32 v242, v242, v180
	v_mul_f32_e32 v36, v36, v180
	v_mul_f32_e32 v243, v243, v180
	v_mul_f32_e32 v37, v37, v180
	v_mul_f32_e32 v244, v244, v180
	v_mul_f32_e32 v38, v38, v180
	v_mul_f32_e32 v245, v245, v180
	v_mul_f32_e32 v39, v39, v180
	v_fma_f32 v238, v238, v104, v134
	v_fma_f32 v32, v32, v105, v135
	v_fma_f32 v239, v239, v106, v136
	v_fma_f32 v33, v33, v107, v137
	v_fma_f32 v240, v240, v108, v138
	v_fma_f32 v34, v34, v109, v139
	v_fma_f32 v241, v241, v110, v140
	v_fma_f32 v35, v35, v111, v141
	v_fma_f32 v242, v242, v112, v142
	v_fma_f32 v36, v36, v113, v143
	v_fma_f32 v243, v243, v114, v144
	v_fma_f32 v37, v37, v115, v145
	v_fma_f32 v244, v244, v116, v146
	v_fma_f32 v38, v38, v117, v147
	v_fma_f32 v245, v245, v118, v148
	v_fma_f32 v39, v39, v119, v149
	v_cvt_pk_bf16_f32 v150, v238, v32
	v_cvt_pk_bf16_f32 v151, v239, v33
	global_store_dwordx2 v0, v[150:151], s[8:9] offset:0
	v_cvt_pk_bf16_f32 v152, v240, v34
	v_cvt_pk_bf16_f32 v153, v241, v35
	global_store_dwordx2 v0, v[152:153], s[8:9] offset:512
	v_cvt_pk_bf16_f32 v154, v242, v36
	v_cvt_pk_bf16_f32 v155, v243, v37
	global_store_dwordx2 v0, v[154:155], s[8:9] offset:1024
	v_cvt_pk_bf16_f32 v156, v244, v38
	v_cvt_pk_bf16_f32 v157, v245, v39
	global_store_dwordx2 v0, v[156:157], s[8:9] offset:1536
	s_waitcnt vmcnt(36)
	v_lshlrev_b32_e32 v246, 16, v40
	v_and_b32_e32 v40, 0xffff0000, v40
	v_lshlrev_b32_e32 v247, 16, v41
	v_and_b32_e32 v41, 0xffff0000, v41
	v_lshlrev_b32_e32 v248, 16, v42
	v_and_b32_e32 v42, 0xffff0000, v42
	v_lshlrev_b32_e32 v249, 16, v43
	v_and_b32_e32 v43, 0xffff0000, v43
	v_lshlrev_b32_e32 v250, 16, v44
	v_and_b32_e32 v44, 0xffff0000, v44
	v_lshlrev_b32_e32 v251, 16, v45
	v_and_b32_e32 v45, 0xffff0000, v45
	v_lshlrev_b32_e32 v176, 16, v46
	v_and_b32_e32 v46, 0xffff0000, v46
	v_lshlrev_b32_e32 v177, 16, v47
	v_and_b32_e32 v47, 0xffff0000, v47
	v_mul_f32_e32 v178, v246, v246
	v_fmac_f32_e32 v178, v40, v40
	v_fmac_f32_e32 v178, v247, v247
	v_fmac_f32_e32 v178, v41, v41
	v_fmac_f32_e32 v178, v248, v248
	v_fmac_f32_e32 v178, v42, v42
	v_fmac_f32_e32 v178, v249, v249
	v_fmac_f32_e32 v178, v43, v43
	v_fmac_f32_e32 v178, v250, v250
	v_fmac_f32_e32 v178, v44, v44
	v_fmac_f32_e32 v178, v251, v251
	v_fmac_f32_e32 v178, v45, v45
	v_fmac_f32_e32 v178, v176, v176
	v_fmac_f32_e32 v178, v46, v46
	v_fmac_f32_e32 v178, v177, v177
	v_fmac_f32_e32 v178, v47, v47
	s_waitcnt vmcnt(32)
	v_lshlrev_b32_e32 v238, 16, v48
	v_and_b32_e32 v48, 0xffff0000, v48
	v_add_f32_dpp v178, v178, v178 quad_perm:[1,0,3,2] row_mask:0xf bank_mask:0xf bound_ctrl:1
	v_lshlrev_b32_e32 v239, 16, v49
	v_and_b32_e32 v49, 0xffff0000, v49
	v_add_f32_dpp v178, v178, v178 quad_perm:[2,3,0,1] row_mask:0xf bank_mask:0xf bound_ctrl:1
	v_lshlrev_b32_e32 v240, 16, v50
	v_and_b32_e32 v50, 0xffff0000, v50
	v_add_f32_dpp v178, v178, v178 row_half_mirror row_mask:0xf bank_mask:0xf bound_ctrl:1
	v_lshlrev_b32_e32 v241, 16, v51
	v_and_b32_e32 v51, 0xffff0000, v51
	v_add_f32_dpp v178, v178, v178 row_mirror row_mask:0xf bank_mask:0xf bound_ctrl:1
	v_lshlrev_b32_e32 v242, 16, v52
	v_and_b32_e32 v52, 0xffff0000, v52
	v_add_f32_dpp v178, v178, v178 row_bcast:15 row_mask:0xa bank_mask:0xf
	v_lshlrev_b32_e32 v243, 16, v53
	v_and_b32_e32 v53, 0xffff0000, v53
	v_add_f32_dpp v178, v178, v178 row_bcast:31 row_mask:0xc bank_mask:0xf
	v_lshlrev_b32_e32 v244, 16, v54
	v_and_b32_e32 v54, 0xffff0000, v54
	v_lshlrev_b32_e32 v245, 16, v55
	v_and_b32_e32 v55, 0xffff0000, v55
	v_readlane_b32 s0, v178, 63
	s_nop 1
	v_mov_b32_e32 v181, s0
	v_fmamk_f32 v181, v181, 0x3a800000, v161
	v_rsq_f32_e32 v179, v181
	s_nop 0
	v_mul_f32_e32 v246, v246, v179
	v_mul_f32_e32 v40, v40, v179
	v_mul_f32_e32 v247, v247, v179
	v_mul_f32_e32 v41, v41, v179
	v_mul_f32_e32 v248, v248, v179
	v_mul_f32_e32 v42, v42, v179
	v_mul_f32_e32 v249, v249, v179
	v_mul_f32_e32 v43, v43, v179
	v_mul_f32_e32 v250, v250, v179
	v_mul_f32_e32 v44, v44, v179
	v_mul_f32_e32 v251, v251, v179
	v_mul_f32_e32 v45, v45, v179
	v_mul_f32_e32 v176, v176, v179
	v_mul_f32_e32 v46, v46, v179
	v_mul_f32_e32 v177, v177, v179
	v_mul_f32_e32 v47, v47, v179
	v_fmac_f32_e32 v238, v88, v246
	v_fmac_f32_e32 v48, v89, v40
	v_fmac_f32_e32 v239, v90, v247
	v_fmac_f32_e32 v49, v91, v41
	v_fmac_f32_e32 v240, v92, v248
	v_fmac_f32_e32 v50, v93, v42
	v_fmac_f32_e32 v241, v94, v249
	v_fmac_f32_e32 v51, v95, v43
	v_fmac_f32_e32 v242, v96, v250
	v_fmac_f32_e32 v52, v97, v44
	v_fmac_f32_e32 v243, v98, v251
	v_fmac_f32_e32 v53, v99, v45
	v_fmac_f32_e32 v244, v100, v176
	v_fmac_f32_e32 v54, v101, v46
	v_fmac_f32_e32 v245, v102, v177
	v_fmac_f32_e32 v55, v103, v47
	v_cvt_pk_bf16_f32 v120, v238, v48
	v_cvt_pk_bf16_f32 v121, v239, v49
	global_store_dwordx2 v2, v[120:121], s[4:5] offset:0 nt
	v_cvt_pk_bf16_f32 v122, v240, v50
	v_cvt_pk_bf16_f32 v123, v241, v51
	global_store_dwordx2 v2, v[122:123], s[4:5] offset:512 nt
	v_cvt_pk_bf16_f32 v124, v242, v52
	v_cvt_pk_bf16_f32 v125, v243, v53
	global_store_dwordx2 v2, v[124:125], s[4:5] offset:1024 nt
	v_cvt_pk_bf16_f32 v126, v244, v54
	v_cvt_pk_bf16_f32 v127, v245, v55
	global_store_dwordx2 v2, v[126:127], s[4:5] offset:1536 nt
	v_mul_f32_e32 v178, v238, v238
	v_fmac_f32_e32 v178, v48, v48
	v_fmac_f32_e32 v178, v239, v239
	v_fmac_f32_e32 v178, v49, v49
	v_fmac_f32_e32 v178, v240, v240
	v_fmac_f32_e32 v178, v50, v50
	v_fmac_f32_e32 v178, v241, v241
	v_fmac_f32_e32 v178, v51, v51
	v_fmac_f32_e32 v178, v242, v242
	v_fmac_f32_e32 v178, v52, v52
	v_fmac_f32_e32 v178, v243, v243
	v_fmac_f32_e32 v178, v53, v53
	v_fmac_f32_e32 v178, v244, v244
	v_fmac_f32_e32 v178, v54, v54
	v_fmac_f32_e32 v178, v245, v245
	v_fmac_f32_e32 v178, v55, v55
	s_nop 1
	v_add_f32_dpp v178, v178, v178 quad_perm:[1,0,3,2] row_mask:0xf bank_mask:0xf bound_ctrl:1
	s_nop 1
	v_add_f32_dpp v178, v178, v178 quad_perm:[2,3,0,1] row_mask:0xf bank_mask:0xf bound_ctrl:1
	s_nop 1
	v_add_f32_dpp v178, v178, v178 row_half_mirror row_mask:0xf bank_mask:0xf bound_ctrl:1
	s_nop 1
	v_add_f32_dpp v178, v178, v178 row_mirror row_mask:0xf bank_mask:0xf bound_ctrl:1
	s_nop 1
	v_add_f32_dpp v178, v178, v178 row_bcast:15 row_mask:0xa bank_mask:0xf
	s_nop 1
	v_add_f32_dpp v178, v178, v178 row_bcast:31 row_mask:0xc bank_mask:0xf
	s_nop 0
	v_readlane_b32 s0, v178, 63
	s_nop 1
	v_mov_b32_e32 v181, s0
	v_fmamk_f32 v181, v181, 0x3a800000, v161
	v_rsq_f32_e32 v180, v181
	s_nop 0
	v_mul_f32_e32 v238, v238, v180
	v_mul_f32_e32 v48, v48, v180
	v_mul_f32_e32 v239, v239, v180
	v_mul_f32_e32 v49, v49, v180
	v_mul_f32_e32 v240, v240, v180
	v_mul_f32_e32 v50, v50, v180
	v_mul_f32_e32 v241, v241, v180
	v_mul_f32_e32 v51, v51, v180
	v_mul_f32_e32 v242, v242, v180
	v_mul_f32_e32 v52, v52, v180
	v_mul_f32_e32 v243, v243, v180
	v_mul_f32_e32 v53, v53, v180
	v_mul_f32_e32 v244, v244, v180
	v_mul_f32_e32 v54, v54, v180
	v_mul_f32_e32 v245, v245, v180
	v_mul_f32_e32 v55, v55, v180
	v_fma_f32 v238, v238, v104, v134
	v_fma_f32 v48, v48, v105, v135
	v_fma_f32 v239, v239, v106, v136
	v_fma_f32 v49, v49, v107, v137
	v_fma_f32 v240, v240, v108, v138
	v_fma_f32 v50, v50, v109, v139
	v_fma_f32 v241, v241, v110, v140
	v_fma_f32 v51, v51, v111, v141
	v_fma_f32 v242, v242, v112, v142
	v_fma_f32 v52, v52, v113, v143
	v_fma_f32 v243, v243, v114, v144
	v_fma_f32 v53, v53, v115, v145
	v_fma_f32 v244, v244, v116, v146
	v_fma_f32 v54, v54, v117, v147
	v_fma_f32 v245, v245, v118, v148
	v_fma_f32 v55, v55, v119, v149
	v_cvt_pk_bf16_f32 v150, v238, v48
	v_cvt_pk_bf16_f32 v151, v239, v49
	global_store_dwordx2 v2, v[150:151], s[8:9] offset:0
	v_cvt_pk_bf16_f32 v152, v240, v50
	v_cvt_pk_bf16_f32 v153, v241, v51
	global_store_dwordx2 v2, v[152:153], s[8:9] offset:512
	v_cvt_pk_bf16_f32 v154, v242, v52
	v_cvt_pk_bf16_f32 v155, v243, v53
	global_store_dwordx2 v2, v[154:155], s[8:9] offset:1024
	v_cvt_pk_bf16_f32 v156, v244, v54
	v_cvt_pk_bf16_f32 v157, v245, v55
	global_store_dwordx2 v2, v[156:157], s[8:9] offset:1536
	s_waitcnt vmcnt(28)
	v_lshlrev_b32_e32 v246, 16, v8
	v_and_b32_e32 v8, 0xffff0000, v8
	v_lshlrev_b32_e32 v247, 16, v9
	v_and_b32_e32 v9, 0xffff0000, v9
	v_lshlrev_b32_e32 v248, 16, v10
	v_and_b32_e32 v10, 0xffff0000, v10
	v_lshlrev_b32_e32 v249, 16, v11
	v_and_b32_e32 v11, 0xffff0000, v11
	v_lshlrev_b32_e32 v250, 16, v12
	v_and_b32_e32 v12, 0xffff0000, v12
	v_lshlrev_b32_e32 v251, 16, v13
	v_and_b32_e32 v13, 0xffff0000, v13
	v_lshlrev_b32_e32 v176, 16, v14
	v_and_b32_e32 v14, 0xffff0000, v14
	v_lshlrev_b32_e32 v177, 16, v15
	v_and_b32_e32 v15, 0xffff0000, v15
	v_mul_f32_e32 v178, v246, v246
	v_fmac_f32_e32 v178, v8, v8
	v_fmac_f32_e32 v178, v247, v247
	v_fmac_f32_e32 v178, v9, v9
	v_fmac_f32_e32 v178, v248, v248
	v_fmac_f32_e32 v178, v10, v10
	v_fmac_f32_e32 v178, v249, v249
	v_fmac_f32_e32 v178, v11, v11
	v_fmac_f32_e32 v178, v250, v250
	v_fmac_f32_e32 v178, v12, v12
	v_fmac_f32_e32 v178, v251, v251
	v_fmac_f32_e32 v178, v13, v13
	v_fmac_f32_e32 v178, v176, v176
	v_fmac_f32_e32 v178, v14, v14
	v_fmac_f32_e32 v178, v177, v177
	v_fmac_f32_e32 v178, v15, v15
	s_waitcnt vmcnt(24)
	v_lshlrev_b32_e32 v238, 16, v16
	v_and_b32_e32 v16, 0xffff0000, v16
	v_add_f32_dpp v178, v178, v178 quad_perm:[1,0,3,2] row_mask:0xf bank_mask:0xf bound_ctrl:1
	v_lshlrev_b32_e32 v239, 16, v17
	v_and_b32_e32 v17, 0xffff0000, v17
	v_add_f32_dpp v178, v178, v178 quad_perm:[2,3,0,1] row_mask:0xf bank_mask:0xf bound_ctrl:1
	v_lshlrev_b32_e32 v240, 16, v18
	v_and_b32_e32 v18, 0xffff0000, v18
	v_add_f32_dpp v178, v178, v178 row_half_mirror row_mask:0xf bank_mask:0xf bound_ctrl:1
	v_lshlrev_b32_e32 v241, 16, v19
	v_and_b32_e32 v19, 0xffff0000, v19
	v_add_f32_dpp v178, v178, v178 row_mirror row_mask:0xf bank_mask:0xf bound_ctrl:1
	v_lshlrev_b32_e32 v242, 16, v20
	v_and_b32_e32 v20, 0xffff0000, v20
	v_add_f32_dpp v178, v178, v178 row_bcast:15 row_mask:0xa bank_mask:0xf
	v_lshlrev_b32_e32 v243, 16, v21
	v_and_b32_e32 v21, 0xffff0000, v21
	v_add_f32_dpp v178, v178, v178 row_bcast:31 row_mask:0xc bank_mask:0xf
	v_lshlrev_b32_e32 v244, 16, v22
	v_and_b32_e32 v22, 0xffff0000, v22
	v_lshlrev_b32_e32 v245, 16, v23
	v_and_b32_e32 v23, 0xffff0000, v23
	v_readlane_b32 s0, v178, 63
	s_nop 1
	v_mov_b32_e32 v181, s0
	v_fmamk_f32 v181, v181, 0x3a800000, v161
	v_rsq_f32_e32 v179, v181
	s_nop 0
	v_mul_f32_e32 v246, v246, v179
	v_mul_f32_e32 v8, v8, v179
	v_mul_f32_e32 v247, v247, v179
	v_mul_f32_e32 v9, v9, v179
	v_mul_f32_e32 v248, v248, v179
	v_mul_f32_e32 v10, v10, v179
	v_mul_f32_e32 v249, v249, v179
	v_mul_f32_e32 v11, v11, v179
	v_mul_f32_e32 v250, v250, v179
	v_mul_f32_e32 v12, v12, v179
	v_mul_f32_e32 v251, v251, v179
	v_mul_f32_e32 v13, v13, v179
	v_mul_f32_e32 v176, v176, v179
	v_mul_f32_e32 v14, v14, v179
	v_mul_f32_e32 v177, v177, v179
	v_mul_f32_e32 v15, v15, v179
	v_fmac_f32_e32 v238, v88, v246
	v_fmac_f32_e32 v16, v89, v8
	v_fmac_f32_e32 v239, v90, v247
	v_fmac_f32_e32 v17, v91, v9
	v_fmac_f32_e32 v240, v92, v248
	v_fmac_f32_e32 v18, v93, v10
	v_fmac_f32_e32 v241, v94, v249
	v_fmac_f32_e32 v19, v95, v11
	v_fmac_f32_e32 v242, v96, v250
	v_fmac_f32_e32 v20, v97, v12
	v_fmac_f32_e32 v243, v98, v251
	v_fmac_f32_e32 v21, v99, v13
	v_fmac_f32_e32 v244, v100, v176
	v_fmac_f32_e32 v22, v101, v14
	v_fmac_f32_e32 v245, v102, v177
	v_fmac_f32_e32 v23, v103, v15
	v_cvt_pk_bf16_f32 v120, v238, v16
	v_cvt_pk_bf16_f32 v121, v239, v17
	global_store_dwordx2 v3, v[120:121], s[4:5] offset:0 nt
	v_cvt_pk_bf16_f32 v122, v240, v18
	v_cvt_pk_bf16_f32 v123, v241, v19
	global_store_dwordx2 v3, v[122:123], s[4:5] offset:512 nt
	v_cvt_pk_bf16_f32 v124, v242, v20
	v_cvt_pk_bf16_f32 v125, v243, v21
	global_store_dwordx2 v3, v[124:125], s[4:5] offset:1024 nt
	v_cvt_pk_bf16_f32 v126, v244, v22
	v_cvt_pk_bf16_f32 v127, v245, v23
	global_store_dwordx2 v3, v[126:127], s[4:5] offset:1536 nt
	v_mul_f32_e32 v178, v238, v238
	v_fmac_f32_e32 v178, v16, v16
	v_fmac_f32_e32 v178, v239, v239
	v_fmac_f32_e32 v178, v17, v17
	v_fmac_f32_e32 v178, v240, v240
	v_fmac_f32_e32 v178, v18, v18
	v_fmac_f32_e32 v178, v241, v241
	v_fmac_f32_e32 v178, v19, v19
	v_fmac_f32_e32 v178, v242, v242
	v_fmac_f32_e32 v178, v20, v20
	v_fmac_f32_e32 v178, v243, v243
	v_fmac_f32_e32 v178, v21, v21
	v_fmac_f32_e32 v178, v244, v244
	v_fmac_f32_e32 v178, v22, v22
	v_fmac_f32_e32 v178, v245, v245
	v_fmac_f32_e32 v178, v23, v23
	s_nop 1
	v_add_f32_dpp v178, v178, v178 quad_perm:[1,0,3,2] row_mask:0xf bank_mask:0xf bound_ctrl:1
	s_nop 1
	v_add_f32_dpp v178, v178, v178 quad_perm:[2,3,0,1] row_mask:0xf bank_mask:0xf bound_ctrl:1
	s_nop 1
	v_add_f32_dpp v178, v178, v178 row_half_mirror row_mask:0xf bank_mask:0xf bound_ctrl:1
	s_nop 1
	v_add_f32_dpp v178, v178, v178 row_mirror row_mask:0xf bank_mask:0xf bound_ctrl:1
	s_nop 1
	v_add_f32_dpp v178, v178, v178 row_bcast:15 row_mask:0xa bank_mask:0xf
	s_nop 1
	v_add_f32_dpp v178, v178, v178 row_bcast:31 row_mask:0xc bank_mask:0xf
	s_nop 0
	v_readlane_b32 s0, v178, 63
	s_nop 1
	v_mov_b32_e32 v181, s0
	v_fmamk_f32 v181, v181, 0x3a800000, v161
	v_rsq_f32_e32 v180, v181
	s_nop 0
	v_mul_f32_e32 v238, v238, v180
	v_mul_f32_e32 v16, v16, v180
	v_mul_f32_e32 v239, v239, v180
	v_mul_f32_e32 v17, v17, v180
	v_mul_f32_e32 v240, v240, v180
	v_mul_f32_e32 v18, v18, v180
	v_mul_f32_e32 v241, v241, v180
	v_mul_f32_e32 v19, v19, v180
	v_mul_f32_e32 v242, v242, v180
	v_mul_f32_e32 v20, v20, v180
	v_mul_f32_e32 v243, v243, v180
	v_mul_f32_e32 v21, v21, v180
	v_mul_f32_e32 v244, v244, v180
	v_mul_f32_e32 v22, v22, v180
	v_mul_f32_e32 v245, v245, v180
	v_mul_f32_e32 v23, v23, v180
	v_fma_f32 v238, v238, v104, v134
	v_fma_f32 v16, v16, v105, v135
	v_fma_f32 v239, v239, v106, v136
	v_fma_f32 v17, v17, v107, v137
	v_fma_f32 v240, v240, v108, v138
	v_fma_f32 v18, v18, v109, v139
	v_fma_f32 v241, v241, v110, v140
	v_fma_f32 v19, v19, v111, v141
	v_fma_f32 v242, v242, v112, v142
	v_fma_f32 v20, v20, v113, v143
	v_fma_f32 v243, v243, v114, v144
	v_fma_f32 v21, v21, v115, v145
	v_fma_f32 v244, v244, v116, v146
	v_fma_f32 v22, v22, v117, v147
	v_fma_f32 v245, v245, v118, v148
	v_fma_f32 v23, v23, v119, v149
	v_cvt_pk_bf16_f32 v150, v238, v16
	v_cvt_pk_bf16_f32 v151, v239, v17
	global_store_dwordx2 v3, v[150:151], s[8:9] offset:0
	v_cvt_pk_bf16_f32 v152, v240, v18
	v_cvt_pk_bf16_f32 v153, v241, v19
	global_store_dwordx2 v3, v[152:153], s[8:9] offset:512
	v_cvt_pk_bf16_f32 v154, v242, v20
	v_cvt_pk_bf16_f32 v155, v243, v21
	global_store_dwordx2 v3, v[154:155], s[8:9] offset:1024
	v_cvt_pk_bf16_f32 v156, v244, v22
	v_cvt_pk_bf16_f32 v157, v245, v23
	global_store_dwordx2 v3, v[156:157], s[8:9] offset:1536
	s_waitcnt vmcnt(28)
	v_lshlrev_b32_e32 v246, 16, v190
	v_and_b32_e32 v190, 0xffff0000, v190
	v_lshlrev_b32_e32 v247, 16, v191
	v_and_b32_e32 v191, 0xffff0000, v191
	v_lshlrev_b32_e32 v248, 16, v192
	v_and_b32_e32 v192, 0xffff0000, v192
	v_lshlrev_b32_e32 v249, 16, v193
	v_and_b32_e32 v193, 0xffff0000, v193
	v_lshlrev_b32_e32 v250, 16, v194
	v_and_b32_e32 v194, 0xffff0000, v194
	v_lshlrev_b32_e32 v251, 16, v195
	v_and_b32_e32 v195, 0xffff0000, v195
	v_lshlrev_b32_e32 v176, 16, v196
	v_and_b32_e32 v196, 0xffff0000, v196
	v_lshlrev_b32_e32 v177, 16, v197
	v_and_b32_e32 v197, 0xffff0000, v197
	v_mul_f32_e32 v178, v246, v246
	v_fmac_f32_e32 v178, v190, v190
	v_fmac_f32_e32 v178, v247, v247
	v_fmac_f32_e32 v178, v191, v191
	v_fmac_f32_e32 v178, v248, v248
	v_fmac_f32_e32 v178, v192, v192
	v_fmac_f32_e32 v178, v249, v249
	v_fmac_f32_e32 v178, v193, v193
	v_fmac_f32_e32 v178, v250, v250
	v_fmac_f32_e32 v178, v194, v194
	v_fmac_f32_e32 v178, v251, v251
	v_fmac_f32_e32 v178, v195, v195
	v_fmac_f32_e32 v178, v176, v176
	v_fmac_f32_e32 v178, v196, v196
	v_fmac_f32_e32 v178, v177, v177
	v_fmac_f32_e32 v178, v197, v197
	s_waitcnt vmcnt(24)
	v_lshlrev_b32_e32 v238, 16, v198
	v_and_b32_e32 v198, 0xffff0000, v198
	v_add_f32_dpp v178, v178, v178 quad_perm:[1,0,3,2] row_mask:0xf bank_mask:0xf bound_ctrl:1
	v_lshlrev_b32_e32 v239, 16, v199
	v_and_b32_e32 v199, 0xffff0000, v199
	v_add_f32_dpp v178, v178, v178 quad_perm:[2,3,0,1] row_mask:0xf bank_mask:0xf bound_ctrl:1
	v_lshlrev_b32_e32 v240, 16, v200
	v_and_b32_e32 v200, 0xffff0000, v200
	v_add_f32_dpp v178, v178, v178 row_half_mirror row_mask:0xf bank_mask:0xf bound_ctrl:1
	v_lshlrev_b32_e32 v241, 16, v201
	v_and_b32_e32 v201, 0xffff0000, v201
	v_add_f32_dpp v178, v178, v178 row_mirror row_mask:0xf bank_mask:0xf bound_ctrl:1
	v_lshlrev_b32_e32 v242, 16, v202
	v_and_b32_e32 v202, 0xffff0000, v202
	v_add_f32_dpp v178, v178, v178 row_bcast:15 row_mask:0xa bank_mask:0xf
	v_lshlrev_b32_e32 v243, 16, v203
	v_and_b32_e32 v203, 0xffff0000, v203
	v_add_f32_dpp v178, v178, v178 row_bcast:31 row_mask:0xc bank_mask:0xf
	v_lshlrev_b32_e32 v244, 16, v204
	v_and_b32_e32 v204, 0xffff0000, v204
	v_lshlrev_b32_e32 v245, 16, v205
	v_and_b32_e32 v205, 0xffff0000, v205
	v_readlane_b32 s0, v178, 63
	s_nop 1
	v_mov_b32_e32 v181, s0
	v_fmamk_f32 v181, v181, 0x3a800000, v161
	v_rsq_f32_e32 v179, v181
	s_nop 0
	v_mul_f32_e32 v246, v246, v179
	v_mul_f32_e32 v190, v190, v179
	v_mul_f32_e32 v247, v247, v179
	v_mul_f32_e32 v191, v191, v179
	v_mul_f32_e32 v248, v248, v179
	v_mul_f32_e32 v192, v192, v179
	v_mul_f32_e32 v249, v249, v179
	v_mul_f32_e32 v193, v193, v179
	v_mul_f32_e32 v250, v250, v179
	v_mul_f32_e32 v194, v194, v179
	v_mul_f32_e32 v251, v251, v179
	v_mul_f32_e32 v195, v195, v179
	v_mul_f32_e32 v176, v176, v179
	v_mul_f32_e32 v196, v196, v179
	v_mul_f32_e32 v177, v177, v179
	v_mul_f32_e32 v197, v197, v179
	v_fmac_f32_e32 v238, v88, v246
	v_fmac_f32_e32 v198, v89, v190
	v_fmac_f32_e32 v239, v90, v247
	v_fmac_f32_e32 v199, v91, v191
	v_fmac_f32_e32 v240, v92, v248
	v_fmac_f32_e32 v200, v93, v192
	v_fmac_f32_e32 v241, v94, v249
	v_fmac_f32_e32 v201, v95, v193
	v_fmac_f32_e32 v242, v96, v250
	v_fmac_f32_e32 v202, v97, v194
	v_fmac_f32_e32 v243, v98, v251
	v_fmac_f32_e32 v203, v99, v195
	v_fmac_f32_e32 v244, v100, v176
	v_fmac_f32_e32 v204, v101, v196
	v_fmac_f32_e32 v245, v102, v177
	v_fmac_f32_e32 v205, v103, v197
	v_cvt_pk_bf16_f32 v120, v238, v198
	v_cvt_pk_bf16_f32 v121, v239, v199
	global_store_dwordx2 v4, v[120:121], s[4:5] offset:0 nt
	v_cvt_pk_bf16_f32 v122, v240, v200
	v_cvt_pk_bf16_f32 v123, v241, v201
	global_store_dwordx2 v4, v[122:123], s[4:5] offset:512 nt
	v_cvt_pk_bf16_f32 v124, v242, v202
	v_cvt_pk_bf16_f32 v125, v243, v203
	global_store_dwordx2 v4, v[124:125], s[4:5] offset:1024 nt
	v_cvt_pk_bf16_f32 v126, v244, v204
	v_cvt_pk_bf16_f32 v127, v245, v205
	global_store_dwordx2 v4, v[126:127], s[4:5] offset:1536 nt
	v_mul_f32_e32 v178, v238, v238
	v_fmac_f32_e32 v178, v198, v198
	v_fmac_f32_e32 v178, v239, v239
	v_fmac_f32_e32 v178, v199, v199
	v_fmac_f32_e32 v178, v240, v240
	v_fmac_f32_e32 v178, v200, v200
	v_fmac_f32_e32 v178, v241, v241
	v_fmac_f32_e32 v178, v201, v201
	v_fmac_f32_e32 v178, v242, v242
	v_fmac_f32_e32 v178, v202, v202
	v_fmac_f32_e32 v178, v243, v243
	v_fmac_f32_e32 v178, v203, v203
	v_fmac_f32_e32 v178, v244, v244
	v_fmac_f32_e32 v178, v204, v204
	v_fmac_f32_e32 v178, v245, v245
	v_fmac_f32_e32 v178, v205, v205
	s_nop 1
	v_add_f32_dpp v178, v178, v178 quad_perm:[1,0,3,2] row_mask:0xf bank_mask:0xf bound_ctrl:1
	s_nop 1
	v_add_f32_dpp v178, v178, v178 quad_perm:[2,3,0,1] row_mask:0xf bank_mask:0xf bound_ctrl:1
	s_nop 1
	v_add_f32_dpp v178, v178, v178 row_half_mirror row_mask:0xf bank_mask:0xf bound_ctrl:1
	s_nop 1
	v_add_f32_dpp v178, v178, v178 row_mirror row_mask:0xf bank_mask:0xf bound_ctrl:1
	s_nop 1
	v_add_f32_dpp v178, v178, v178 row_bcast:15 row_mask:0xa bank_mask:0xf
	s_nop 1
	v_add_f32_dpp v178, v178, v178 row_bcast:31 row_mask:0xc bank_mask:0xf
	s_nop 0
	v_readlane_b32 s0, v178, 63
	s_nop 1
	v_mov_b32_e32 v181, s0
	v_fmamk_f32 v181, v181, 0x3a800000, v161
	v_rsq_f32_e32 v180, v181
	s_nop 0
	v_mul_f32_e32 v238, v238, v180
	v_mul_f32_e32 v198, v198, v180
	v_mul_f32_e32 v239, v239, v180
	v_mul_f32_e32 v199, v199, v180
	v_mul_f32_e32 v240, v240, v180
	v_mul_f32_e32 v200, v200, v180
	v_mul_f32_e32 v241, v241, v180
	v_mul_f32_e32 v201, v201, v180
	v_mul_f32_e32 v242, v242, v180
	v_mul_f32_e32 v202, v202, v180
	v_mul_f32_e32 v243, v243, v180
	v_mul_f32_e32 v203, v203, v180
	v_mul_f32_e32 v244, v244, v180
	v_mul_f32_e32 v204, v204, v180
	v_mul_f32_e32 v245, v245, v180
	v_mul_f32_e32 v205, v205, v180
	v_fma_f32 v238, v238, v104, v134
	v_fma_f32 v198, v198, v105, v135
	v_fma_f32 v239, v239, v106, v136
	v_fma_f32 v199, v199, v107, v137
	v_fma_f32 v240, v240, v108, v138
	v_fma_f32 v200, v200, v109, v139
	v_fma_f32 v241, v241, v110, v140
	v_fma_f32 v201, v201, v111, v141
	v_fma_f32 v242, v242, v112, v142
	v_fma_f32 v202, v202, v113, v143
	v_fma_f32 v243, v243, v114, v144
	v_fma_f32 v203, v203, v115, v145
	v_fma_f32 v244, v244, v116, v146
	v_fma_f32 v204, v204, v117, v147
	v_fma_f32 v245, v245, v118, v148
	v_fma_f32 v205, v205, v119, v149
	v_cvt_pk_bf16_f32 v150, v238, v198
	v_cvt_pk_bf16_f32 v151, v239, v199
	global_store_dwordx2 v4, v[150:151], s[8:9] offset:0
	v_cvt_pk_bf16_f32 v152, v240, v200
	v_cvt_pk_bf16_f32 v153, v241, v201
	global_store_dwordx2 v4, v[152:153], s[8:9] offset:512
	v_cvt_pk_bf16_f32 v154, v242, v202
	v_cvt_pk_bf16_f32 v155, v243, v203
	global_store_dwordx2 v4, v[154:155], s[8:9] offset:1024
	v_cvt_pk_bf16_f32 v156, v244, v204
	v_cvt_pk_bf16_f32 v157, v245, v205
	global_store_dwordx2 v4, v[156:157], s[8:9] offset:1536
	s_branch .LBB0_100
.Lrow2_last:
	v_readfirstlane_b32 s0, v160
	v_readlane_b32 s1, v252, 7
	s_lshr_b32 s0, s0, 6
	s_mov_b32 s73, s0
	s_add_i32 s0, s0, s1
	v_readlane_b32 s62, v254, 34
	s_sub_u32 s64, s78, 0x110
	s_subb_u32 s65, s79, 0
	s_load_dwordx2 s[66:67], s[64:65], 0x40
	s_load_dwordx2 s[10:11], s[64:65], 0xf8
	s_lshl_b32 s63, s0, 11
	s_add_u32 s4, s84, 0x167ca000
	s_addc_u32 s5, s85, 0
	s_add_u32 s4, s4, s63
	s_addc_u32 s5, s5, 0
	s_add_u32 s6, s84, 0x112ca000
	s_addc_u32 s7, s85, 0
	s_add_u32 s6, s6, s63
	s_addc_u32 s7, s7, 0
	v_and_b32_e32 v0, 63, v160
	v_lshlrev_b32_e32 v1, 4, v0
	v_lshlrev_b32_e32 v0, 3, v0
	v_add_u32_e32 v2, 0x400000, v0
	v_add_u32_e32 v3, 0x800000, v0
	v_add_u32_e32 v4, 0xc00000, v0
	v_add_u32_e32 v5, 0x1000000, v0
	global_load_dwordx2 v[8:9], v5, s[6:7] offset:0 nt
	global_load_dwordx2 v[10:11], v5, s[6:7] offset:512 nt
	global_load_dwordx2 v[12:13], v5, s[6:7] offset:1024 nt
	global_load_dwordx2 v[14:15], v5, s[6:7] offset:1536 nt
	global_load_dwordx2 v[16:17], v5, s[4:5] offset:0 nt
	global_load_dwordx2 v[18:19], v5, s[4:5] offset:512 nt
	global_load_dwordx2 v[20:21], v5, s[4:5] offset:1024 nt
	global_load_dwordx2 v[22:23], v5, s[4:5] offset:1536 nt
	s_add_u32 s8, s84, 0xaeca000
	s_addc_u32 s9, s85, 0
	s_add_u32 s8, s8, s63
	s_addc_u32 s9, s9, 0
	s_lshr_b32 s69, s0, 10
	s_add_i32 s69, s69, 1
	s_mul_i32 s69, s69, 0x6000
	s_mul_i32 s68, s62, 0x12000
	s_mov_b32 s70, 0
	s_mul_i32 s71, s70, 0x12000
	s_lshl_b32 s70, s70, 14
	s_lshl_b32 s72, s62, 14
	s_add_i32 s72, s72, 0x3000
	s_add_u32 s16, s84, 0x6605000
	s_addc_u32 s17, s85, 0
	s_add_u32 s16, s16, s68
	s_addc_u32 s17, s17, 0
	s_add_u32 s20, s84, 0x6600000
	s_addc_u32 s21, s85, 0
	s_add_u32 s20, s20, s71
	s_addc_u32 s21, s21, 0
	s_add_u32 s18, s20, 0x1000
	s_addc_u32 s19, s21, 0
	s_add_u32 s22, s16, s69
	s_addc_u32 s23, s17, 0
	s_add_u32 s60, s20, s69
	s_addc_u32 s61, s21, 0
	s_add_u32 s26, s18, s69
	s_addc_u32 s27, s19, 0
	s_lshl_b32 s63, s63, 1
	s_waitcnt lgkmcnt(0)
	s_add_u32 s12, s66, s72
	s_addc_u32 s13, s67, 0
	s_add_u32 s14, s66, s70
	s_addc_u32 s15, s67, 0
	s_add_u32 s10, s10, s63
	s_addc_u32 s11, s11, 0
	s_mov_b64 s[74:75], s[12:13]
	s_cmp_eq_u32 s73, 1
	s_cselect_b32 s74, s14, s74
	s_cselect_b32 s75, s15, s75
	s_cmp_eq_u32 s73, 2
	s_cselect_b32 s74, s16, s74
	s_cselect_b32 s75, s17, s75
	s_cmp_eq_u32 s73, 3
	s_cselect_b32 s74, s18, s74
	s_cselect_b32 s75, s19, s75
	s_cmp_eq_u32 s73, 4
	s_cselect_b32 s74, s20, s74
	s_cselect_b32 s75, s21, s75
	s_cmp_eq_u32 s73, 5
	s_cselect_b32 s74, s22, s74
	s_cselect_b32 s75, s23, s75
	s_cmp_eq_u32 s73, 6
	s_cselect_b32 s74, s26, s74
	s_cselect_b32 s75, s27, s75
	s_cmp_eq_u32 s73, 7
	s_cselect_b32 s74, s60, s74
	s_cselect_b32 s75, s61, s75
	global_load_dwordx4 v[222:225], v1, s[74:75] offset:0
	global_load_dwordx4 v[226:229], v1, s[74:75] offset:1024
	global_load_dwordx4 v[230:233], v1, s[74:75] offset:2048
	global_load_dwordx4 v[234:237], v1, s[74:75] offset:3072
	s_lshl_b32 s74, s73, 12
	v_add_u32_e32 v6, s74, v1
	global_load_dwordx2 v[24:25], v0, s[6:7] offset:0 nt
	global_load_dwordx2 v[26:27], v0, s[6:7] offset:512 nt
	global_load_dwordx2 v[28:29], v0, s[6:7] offset:1024 nt
	global_load_dwordx2 v[30:31], v0, s[6:7] offset:1536 nt
	global_load_dwordx2 v[32:33], v0, s[4:5] offset:0 nt
	global_load_dwordx2 v[34:35], v0, s[4:5] offset:512 nt
	global_load_dwordx2 v[36:37], v0, s[4:5] offset:1024 nt
	global_load_dwordx2 v[38:39], v0, s[4:5] offset:1536 nt
	global_load_dwordx2 v[40:41], v2, s[6:7] offset:0 nt
	global_load_dwordx2 v[42:43], v2, s[6:7] offset:512 nt
	global_load_dwordx2 v[44:45], v2, s[6:7] offset:1024 nt
	global_load_dwordx2 v[46:47], v2, s[6:7] offset:1536 nt
	global_load_dwordx2 v[48:49], v2, s[4:5] offset:0 nt
	global_load_dwordx2 v[50:51], v2, s[4:5] offset:512 nt
	global_load_dwordx2 v[52:53], v2, s[4:5] offset:1024 nt
	global_load_dwordx2 v[54:55], v2, s[4:5] offset:1536 nt
	s_waitcnt vmcnt(16)
	ds_write_b128 v6, v[222:225] offset:0
	ds_write_b128 v6, v[226:229] offset:1024
	ds_write_b128 v6, v[230:233] offset:2048
	ds_write_b128 v6, v[234:237] offset:3072
	s_waitcnt lgkmcnt(0)
	s_barrier
	ds_read_b128 v[56:59], v1 offset:0
	ds_read_b128 v[60:63], v1 offset:1024
	ds_read_b128 v[64:67], v1 offset:2048
	ds_read_b128 v[68:71], v1 offset:3072
	ds_read_b128 v[88:91], v1 offset:8192
	ds_read_b128 v[92:95], v1 offset:9216
	ds_read_b128 v[96:99], v1 offset:10240
	ds_read_b128 v[100:103], v1 offset:11264
	ds_read_b128 v[190:193], v1 offset:20480
	ds_read_b128 v[194:197], v1 offset:21504
	ds_read_b128 v[198:201], v1 offset:22528
	ds_read_b128 v[202:205], v1 offset:23552
	s_waitcnt lgkmcnt(0)
	v_mul_f32_e32 v190, v190, v56
	v_mul_f32_e32 v191, v191, v57
	v_mul_f32_e32 v192, v192, v58
	v_mul_f32_e32 v193, v193, v59
	v_mul_f32_e32 v194, v194, v60
	v_mul_f32_e32 v195, v195, v61
	v_mul_f32_e32 v196, v196, v62
	v_mul_f32_e32 v197, v197, v63
	v_mul_f32_e32 v198, v198, v64
	v_mul_f32_e32 v199, v199, v65
	v_mul_f32_e32 v200, v200, v66
	v_mul_f32_e32 v201, v201, v67
	v_mul_f32_e32 v202, v202, v68
	v_mul_f32_e32 v203, v203, v69
	v_mul_f32_e32 v204, v204, v70
	v_mul_f32_e32 v205, v205, v71
	v_mul_f32_e32 v88, v88, v56
	v_mul_f32_e32 v89, v89, v57
	v_mul_f32_e32 v90, v90, v58
	v_mul_f32_e32 v91, v91, v59
	v_mul_f32_e32 v92, v92, v60
	v_mul_f32_e32 v93, v93, v61
	v_mul_f32_e32 v94, v94, v62
	v_mul_f32_e32 v95, v95, v63
	v_mul_f32_e32 v96, v96, v64
	v_mul_f32_e32 v97, v97, v65
	v_mul_f32_e32 v98, v98, v66
	v_mul_f32_e32 v99, v99, v67
	v_mul_f32_e32 v100, v100, v68
	v_mul_f32_e32 v101, v101, v69
	v_mul_f32_e32 v102, v102, v70
	v_mul_f32_e32 v103, v103, v71
	v_lshlrev_b32_e32 v246, 16, v8
	v_and_b32_e32 v8, 0xffff0000, v8
	v_lshlrev_b32_e32 v247, 16, v9
	v_and_b32_e32 v9, 0xffff0000, v9
	v_lshlrev_b32_e32 v248, 16, v10
	v_and_b32_e32 v10, 0xffff0000, v10
	v_lshlrev_b32_e32 v249, 16, v11
	v_and_b32_e32 v11, 0xffff0000, v11
	v_lshlrev_b32_e32 v250, 16, v12
	v_and_b32_e32 v12, 0xffff0000, v12
	v_lshlrev_b32_e32 v251, 16, v13
	v_and_b32_e32 v13, 0xffff0000, v13
	v_lshlrev_b32_e32 v176, 16, v14
	v_and_b32_e32 v14, 0xffff0000, v14
	v_lshlrev_b32_e32 v177, 16, v15
	v_and_b32_e32 v15, 0xffff0000, v15
	v_mul_f32_e32 v178, v246, v246
	v_fmac_f32_e32 v178, v8, v8
	v_fmac_f32_e32 v178, v247, v247
	v_fmac_f32_e32 v178, v9, v9
	v_fmac_f32_e32 v178, v248, v248
	v_fmac_f32_e32 v178, v10, v10
	v_fmac_f32_e32 v178, v249, v249
	v_fmac_f32_e32 v178, v11, v11
	v_fmac_f32_e32 v178, v250, v250
	v_fmac_f32_e32 v178, v12, v12
	v_fmac_f32_e32 v178, v251, v251
	v_fmac_f32_e32 v178, v13, v13
	v_fmac_f32_e32 v178, v176, v176
	v_fmac_f32_e32 v178, v14, v14
	v_fmac_f32_e32 v178, v177, v177
	v_fmac_f32_e32 v178, v15, v15
	v_lshlrev_b32_e32 v238, 16, v16
	v_and_b32_e32 v16, 0xffff0000, v16
	v_add_f32_dpp v178, v178, v178 quad_perm:[1,0,3,2] row_mask:0xf bank_mask:0xf bound_ctrl:1
	v_lshlrev_b32_e32 v239, 16, v17
	v_and_b32_e32 v17, 0xffff0000, v17
	v_add_f32_dpp v178, v178, v178 quad_perm:[2,3,0,1] row_mask:0xf bank_mask:0xf bound_ctrl:1
	v_lshlrev_b32_e32 v240, 16, v18
	v_and_b32_e32 v18, 0xffff0000, v18
	v_add_f32_dpp v178, v178, v178 row_half_mirror row_mask:0xf bank_mask:0xf bound_ctrl:1
	v_lshlrev_b32_e32 v241, 16, v19
	v_and_b32_e32 v19, 0xffff0000, v19
	v_add_f32_dpp v178, v178, v178 row_mirror row_mask:0xf bank_mask:0xf bound_ctrl:1
	v_lshlrev_b32_e32 v242, 16, v20
	v_and_b32_e32 v20, 0xffff0000, v20
	v_add_f32_dpp v178, v178, v178 row_bcast:15 row_mask:0xa bank_mask:0xf
	v_lshlrev_b32_e32 v243, 16, v21
	v_and_b32_e32 v21, 0xffff0000, v21
	v_add_f32_dpp v178, v178, v178 row_bcast:31 row_mask:0xc bank_mask:0xf
	v_lshlrev_b32_e32 v244, 16, v22
	v_and_b32_e32 v22, 0xffff0000, v22
	v_lshlrev_b32_e32 v245, 16, v23
	v_and_b32_e32 v23, 0xffff0000, v23
	v_readlane_b32 s0, v178, 63
	s_nop 1
	v_mov_b32_e32 v181, s0
	v_fmamk_f32 v181, v181, 0x3a800000, v161
	v_rsq_f32_e32 v179, v181
	s_nop 0
	s_waitcnt lgkmcnt(0)
	v_mul_f32_e32 v246, v246, v179
	v_mul_f32_e32 v8, v8, v179
	v_mul_f32_e32 v247, v247, v179
	v_mul_f32_e32 v9, v9, v179
	v_mul_f32_e32 v248, v248, v179
	v_mul_f32_e32 v10, v10, v179
	v_mul_f32_e32 v249, v249, v179
	v_mul_f32_e32 v11, v11, v179
	v_mul_f32_e32 v250, v250, v179
	v_mul_f32_e32 v12, v12, v179
	v_mul_f32_e32 v251, v251, v179
	v_mul_f32_e32 v13, v13, v179
	v_mul_f32_e32 v176, v176, v179
	v_mul_f32_e32 v14, v14, v179
	v_mul_f32_e32 v177, v177, v179
	v_mul_f32_e32 v15, v15, v179
	v_fmac_f32_e32 v238, v190, v246
	v_fmac_f32_e32 v16, v191, v8
	v_fmac_f32_e32 v239, v192, v247
	v_fmac_f32_e32 v17, v193, v9
	v_fmac_f32_e32 v240, v194, v248
	v_fmac_f32_e32 v18, v195, v10
	v_fmac_f32_e32 v241, v196, v249
	v_fmac_f32_e32 v19, v197, v11
	v_fmac_f32_e32 v242, v198, v250
	v_fmac_f32_e32 v20, v199, v12
	v_fmac_f32_e32 v243, v200, v251
	v_fmac_f32_e32 v21, v201, v13
	v_fmac_f32_e32 v244, v202, v176
	v_fmac_f32_e32 v22, v203, v14
	v_fmac_f32_e32 v245, v204, v177
	v_fmac_f32_e32 v23, v205, v15
	v_add_u32_e32 v181, 0x2000000, v1
	v_mov_b32_e32 v120, v238
	v_mov_b32_e32 v121, v16
	v_mov_b32_e32 v122, v239
	v_mov_b32_e32 v123, v17
	global_store_dwordx4 v181, v[120:123], s[10:11] offset:0
	v_mov_b32_e32 v124, v240
	v_mov_b32_e32 v125, v18
	v_mov_b32_e32 v126, v241
	v_mov_b32_e32 v127, v19
	global_store_dwordx4 v181, v[124:127], s[10:11] offset:1024
	v_mov_b32_e32 v150, v242
	v_mov_b32_e32 v151, v20
	v_mov_b32_e32 v152, v243
	v_mov_b32_e32 v153, v21
	global_store_dwordx4 v181, v[150:153], s[10:11] offset:2048
	v_mov_b32_e32 v154, v244
	v_mov_b32_e32 v155, v22
	v_mov_b32_e32 v156, v245
	v_mov_b32_e32 v157, v23
	global_store_dwordx4 v181, v[154:157], s[10:11] offset:3072
	global_load_dwordx2 v[8:9], v3, s[6:7] offset:0 nt
	global_load_dwordx2 v[10:11], v3, s[6:7] offset:512 nt
	global_load_dwordx2 v[12:13], v3, s[6:7] offset:1024 nt
	global_load_dwordx2 v[14:15], v3, s[6:7] offset:1536 nt
	global_load_dwordx2 v[16:17], v3, s[4:5] offset:0 nt
	global_load_dwordx2 v[18:19], v3, s[4:5] offset:512 nt
	global_load_dwordx2 v[20:21], v3, s[4:5] offset:1024 nt
	global_load_dwordx2 v[22:23], v3, s[4:5] offset:1536 nt
	global_load_dwordx2 v[190:191], v4, s[6:7] offset:0 nt
	global_load_dwordx2 v[192:193], v4, s[6:7] offset:512 nt
	global_load_dwordx2 v[194:195], v4, s[6:7] offset:1024 nt
	global_load_dwordx2 v[196:197], v4, s[6:7] offset:1536 nt
	global_load_dwordx2 v[198:199], v4, s[4:5] offset:0 nt
	global_load_dwordx2 v[200:201], v4, s[4:5] offset:512 nt
	global_load_dwordx2 v[202:203], v4, s[4:5] offset:1024 nt
	global_load_dwordx2 v[204:205], v4, s[4:5] offset:1536 nt
	s_waitcnt vmcnt(32)
	v_lshlrev_b32_e32 v246, 16, v24
	v_and_b32_e32 v24, 0xffff0000, v24
	v_lshlrev_b32_e32 v247, 16, v25
	v_and_b32_e32 v25, 0xffff0000, v25
	v_lshlrev_b32_e32 v248, 16, v26
	v_and_b32_e32 v26, 0xffff0000, v26
	v_lshlrev_b32_e32 v249, 16, v27
	v_and_b32_e32 v27, 0xffff0000, v27
	v_lshlrev_b32_e32 v250, 16, v28
	v_and_b32_e32 v28, 0xffff0000, v28
	v_lshlrev_b32_e32 v251, 16, v29
	v_and_b32_e32 v29, 0xffff0000, v29
	v_lshlrev_b32_e32 v176, 16, v30
	v_and_b32_e32 v30, 0xffff0000, v30
	v_lshlrev_b32_e32 v177, 16, v31
	v_and_b32_e32 v31, 0xffff0000, v31
	v_mul_f32_e32 v178, v246, v246
	v_fmac_f32_e32 v178, v24, v24
	v_fmac_f32_e32 v178, v247, v247
	v_fmac_f32_e32 v178, v25, v25
	v_fmac_f32_e32 v178, v248, v248
	v_fmac_f32_e32 v178, v26, v26
	v_fmac_f32_e32 v178, v249, v249
	v_fmac_f32_e32 v178, v27, v27
	v_fmac_f32_e32 v178, v250, v250
	v_fmac_f32_e32 v178, v28, v28
	v_fmac_f32_e32 v178, v251, v251
	v_fmac_f32_e32 v178, v29, v29
	v_fmac_f32_e32 v178, v176, v176
	v_fmac_f32_e32 v178, v30, v30
	v_fmac_f32_e32 v178, v177, v177
	v_fmac_f32_e32 v178, v31, v31
	s_waitcnt vmcnt(28)
	v_lshlrev_b32_e32 v238, 16, v32
	v_and_b32_e32 v32, 0xffff0000, v32
	v_add_f32_dpp v178, v178, v178 quad_perm:[1,0,3,2] row_mask:0xf bank_mask:0xf bound_ctrl:1
	v_lshlrev_b32_e32 v239, 16, v33
	v_and_b32_e32 v33, 0xffff0000, v33
	v_add_f32_dpp v178, v178, v178 quad_perm:[2,3,0,1] row_mask:0xf bank_mask:0xf bound_ctrl:1
	v_lshlrev_b32_e32 v240, 16, v34
	v_and_b32_e32 v34, 0xffff0000, v34
	v_add_f32_dpp v178, v178, v178 row_half_mirror row_mask:0xf bank_mask:0xf bound_ctrl:1
	v_lshlrev_b32_e32 v241, 16, v35
	v_and_b32_e32 v35, 0xffff0000, v35
	v_add_f32_dpp v178, v178, v178 row_mirror row_mask:0xf bank_mask:0xf bound_ctrl:1
	v_lshlrev_b32_e32 v242, 16, v36
	v_and_b32_e32 v36, 0xffff0000, v36
	v_add_f32_dpp v178, v178, v178 row_bcast:15 row_mask:0xa bank_mask:0xf
	v_lshlrev_b32_e32 v243, 16, v37
	v_and_b32_e32 v37, 0xffff0000, v37
	v_add_f32_dpp v178, v178, v178 row_bcast:31 row_mask:0xc bank_mask:0xf
	v_lshlrev_b32_e32 v244, 16, v38
	v_and_b32_e32 v38, 0xffff0000, v38
	v_lshlrev_b32_e32 v245, 16, v39
	v_and_b32_e32 v39, 0xffff0000, v39
	v_readlane_b32 s0, v178, 63
	s_nop 1
	v_mov_b32_e32 v181, s0
	v_fmamk_f32 v181, v181, 0x3a800000, v161
	v_rsq_f32_e32 v179, v181
	s_nop 0
	v_mul_f32_e32 v246, v246, v179
	v_mul_f32_e32 v24, v24, v179
	v_mul_f32_e32 v247, v247, v179
	v_mul_f32_e32 v25, v25, v179
	v_mul_f32_e32 v248, v248, v179
	v_mul_f32_e32 v26, v26, v179
	v_mul_f32_e32 v249, v249, v179
	v_mul_f32_e32 v27, v27, v179
	v_mul_f32_e32 v250, v250, v179
	v_mul_f32_e32 v28, v28, v179
	v_mul_f32_e32 v251, v251, v179
	v_mul_f32_e32 v29, v29, v179
	v_mul_f32_e32 v176, v176, v179
	v_mul_f32_e32 v30, v30, v179
	v_mul_f32_e32 v177, v177, v179
	v_mul_f32_e32 v31, v31, v179
	v_fmac_f32_e32 v238, v88, v246
	v_fmac_f32_e32 v32, v89, v24
	v_fmac_f32_e32 v239, v90, v247
	v_fmac_f32_e32 v33, v91, v25
	v_fmac_f32_e32 v240, v92, v248
	v_fmac_f32_e32 v34, v93, v26
	v_fmac_f32_e32 v241, v94, v249
	v_fmac_f32_e32 v35, v95, v27
	v_fmac_f32_e32 v242, v96, v250
	v_fmac_f32_e32 v36, v97, v28
	v_fmac_f32_e32 v243, v98, v251
	v_fmac_f32_e32 v37, v99, v29
	v_fmac_f32_e32 v244, v100, v176
	v_fmac_f32_e32 v38, v101, v30
	v_fmac_f32_e32 v245, v102, v177
	v_fmac_f32_e32 v39, v103, v31
	v_add_u32_e32 v181, 0x0, v1
	v_mov_b32_e32 v120, v238
	v_mov_b32_e32 v121, v32
	v_mov_b32_e32 v122, v239
	v_mov_b32_e32 v123, v33
	global_store_dwordx4 v181, v[120:123], s[10:11] offset:0
	v_mov_b32_e32 v124, v240
	v_mov_b32_e32 v125, v34
	v_mov_b32_e32 v126, v241
	v_mov_b32_e32 v127, v35
	global_store_dwordx4 v181, v[124:127], s[10:11] offset:1024
	v_mov_b32_e32 v150, v242
	v_mov_b32_e32 v151, v36
	v_mov_b32_e32 v152, v243
	v_mov_b32_e32 v153, v37
	global_store_dwordx4 v181, v[150:153], s[10:11] offset:2048
	v_mov_b32_e32 v154, v244
	v_mov_b32_e32 v155, v38
	v_mov_b32_e32 v156, v245
	v_mov_b32_e32 v157, v39
	global_store_dwordx4 v181, v[154:157], s[10:11] offset:3072
	s_waitcnt vmcnt(28)
	v_lshlrev_b32_e32 v246, 16, v40
	v_and_b32_e32 v40, 0xffff0000, v40
	v_lshlrev_b32_e32 v247, 16, v41
	v_and_b32_e32 v41, 0xffff0000, v41
	v_lshlrev_b32_e32 v248, 16, v42
	v_and_b32_e32 v42, 0xffff0000, v42
	v_lshlrev_b32_e32 v249, 16, v43
	v_and_b32_e32 v43, 0xffff0000, v43
	v_lshlrev_b32_e32 v250, 16, v44
	v_and_b32_e32 v44, 0xffff0000, v44
	v_lshlrev_b32_e32 v251, 16, v45
	v_and_b32_e32 v45, 0xffff0000, v45
	v_lshlrev_b32_e32 v176, 16, v46
	v_and_b32_e32 v46, 0xffff0000, v46
	v_lshlrev_b32_e32 v177, 16, v47
	v_and_b32_e32 v47, 0xffff0000, v47
	v_mul_f32_e32 v178, v246, v246
	v_fmac_f32_e32 v178, v40, v40
	v_fmac_f32_e32 v178, v247, v247
	v_fmac_f32_e32 v178, v41, v41
	v_fmac_f32_e32 v178, v248, v248
	v_fmac_f32_e32 v178, v42, v42
	v_fmac_f32_e32 v178, v249, v249
	v_fmac_f32_e32 v178, v43, v43
	v_fmac_f32_e32 v178, v250, v250
	v_fmac_f32_e32 v178, v44, v44
	v_fmac_f32_e32 v178, v251, v251
	v_fmac_f32_e32 v178, v45, v45
	v_fmac_f32_e32 v178, v176, v176
	v_fmac_f32_e32 v178, v46, v46
	v_fmac_f32_e32 v178, v177, v177
	v_fmac_f32_e32 v178, v47, v47
	s_waitcnt vmcnt(24)
	v_lshlrev_b32_e32 v238, 16, v48
	v_and_b32_e32 v48, 0xffff0000, v48
	v_add_f32_dpp v178, v178, v178 quad_perm:[1,0,3,2] row_mask:0xf bank_mask:0xf bound_ctrl:1
	v_lshlrev_b32_e32 v239, 16, v49
	v_and_b32_e32 v49, 0xffff0000, v49
	v_add_f32_dpp v178, v178, v178 quad_perm:[2,3,0,1] row_mask:0xf bank_mask:0xf bound_ctrl:1
	v_lshlrev_b32_e32 v240, 16, v50
	v_and_b32_e32 v50, 0xffff0000, v50
	v_add_f32_dpp v178, v178, v178 row_half_mirror row_mask:0xf bank_mask:0xf bound_ctrl:1
	v_lshlrev_b32_e32 v241, 16, v51
	v_and_b32_e32 v51, 0xffff0000, v51
	v_add_f32_dpp v178, v178, v178 row_mirror row_mask:0xf bank_mask:0xf bound_ctrl:1
	v_lshlrev_b32_e32 v242, 16, v52
	v_and_b32_e32 v52, 0xffff0000, v52
	v_add_f32_dpp v178, v178, v178 row_bcast:15 row_mask:0xa bank_mask:0xf
	v_lshlrev_b32_e32 v243, 16, v53
	v_and_b32_e32 v53, 0xffff0000, v53
	v_add_f32_dpp v178, v178, v178 row_bcast:31 row_mask:0xc bank_mask:0xf
	v_lshlrev_b32_e32 v244, 16, v54
	v_and_b32_e32 v54, 0xffff0000, v54
	v_lshlrev_b32_e32 v245, 16, v55
	v_and_b32_e32 v55, 0xffff0000, v55
	v_readlane_b32 s0, v178, 63
	s_nop 1
	v_mov_b32_e32 v181, s0
	v_fmamk_f32 v181, v181, 0x3a800000, v161
	v_rsq_f32_e32 v179, v181
	s_nop 0
	v_mul_f32_e32 v246, v246, v179
	v_mul_f32_e32 v40, v40, v179
	v_mul_f32_e32 v247, v247, v179
	v_mul_f32_e32 v41, v41, v179
	v_mul_f32_e32 v248, v248, v179
	v_mul_f32_e32 v42, v42, v179
	v_mul_f32_e32 v249, v249, v179
	v_mul_f32_e32 v43, v43, v179
	v_mul_f32_e32 v250, v250, v179
	v_mul_f32_e32 v44, v44, v179
	v_mul_f32_e32 v251, v251, v179
	v_mul_f32_e32 v45, v45, v179
	v_mul_f32_e32 v176, v176, v179
	v_mul_f32_e32 v46, v46, v179
	v_mul_f32_e32 v177, v177, v179
	v_mul_f32_e32 v47, v47, v179
	v_fmac_f32_e32 v238, v88, v246
	v_fmac_f32_e32 v48, v89, v40
	v_fmac_f32_e32 v239, v90, v247
	v_fmac_f32_e32 v49, v91, v41
	v_fmac_f32_e32 v240, v92, v248
	v_fmac_f32_e32 v50, v93, v42
	v_fmac_f32_e32 v241, v94, v249
	v_fmac_f32_e32 v51, v95, v43
	v_fmac_f32_e32 v242, v96, v250
	v_fmac_f32_e32 v52, v97, v44
	v_fmac_f32_e32 v243, v98, v251
	v_fmac_f32_e32 v53, v99, v45
	v_fmac_f32_e32 v244, v100, v176
	v_fmac_f32_e32 v54, v101, v46
	v_fmac_f32_e32 v245, v102, v177
	v_fmac_f32_e32 v55, v103, v47
	v_add_u32_e32 v181, 0x800000, v1
	v_mov_b32_e32 v120, v238
	v_mov_b32_e32 v121, v48
	v_mov_b32_e32 v122, v239
	v_mov_b32_e32 v123, v49
	global_store_dwordx4 v181, v[120:123], s[10:11] offset:0
	v_mov_b32_e32 v124, v240
	v_mov_b32_e32 v125, v50
	v_mov_b32_e32 v126, v241
	v_mov_b32_e32 v127, v51
	global_store_dwordx4 v181, v[124:127], s[10:11] offset:1024
	v_mov_b32_e32 v150, v242
	v_mov_b32_e32 v151, v52
	v_mov_b32_e32 v152, v243
	v_mov_b32_e32 v153, v53
	global_store_dwordx4 v181, v[150:153], s[10:11] offset:2048
	v_mov_b32_e32 v154, v244
	v_mov_b32_e32 v155, v54
	v_mov_b32_e32 v156, v245
	v_mov_b32_e32 v157, v55
	global_store_dwordx4 v181, v[154:157], s[10:11] offset:3072
	s_waitcnt vmcnt(20)
	v_lshlrev_b32_e32 v246, 16, v8
	v_and_b32_e32 v8, 0xffff0000, v8
	v_lshlrev_b32_e32 v247, 16, v9
	v_and_b32_e32 v9, 0xffff0000, v9
	v_lshlrev_b32_e32 v248, 16, v10
	v_and_b32_e32 v10, 0xffff0000, v10
	v_lshlrev_b32_e32 v249, 16, v11
	v_and_b32_e32 v11, 0xffff0000, v11
	v_lshlrev_b32_e32 v250, 16, v12
	v_and_b32_e32 v12, 0xffff0000, v12
	v_lshlrev_b32_e32 v251, 16, v13
	v_and_b32_e32 v13, 0xffff0000, v13
	v_lshlrev_b32_e32 v176, 16, v14
	v_and_b32_e32 v14, 0xffff0000, v14
	v_lshlrev_b32_e32 v177, 16, v15
	v_and_b32_e32 v15, 0xffff0000, v15
	v_mul_f32_e32 v178, v246, v246
	v_fmac_f32_e32 v178, v8, v8
	v_fmac_f32_e32 v178, v247, v247
	v_fmac_f32_e32 v178, v9, v9
	v_fmac_f32_e32 v178, v248, v248
	v_fmac_f32_e32 v178, v10, v10
	v_fmac_f32_e32 v178, v249, v249
	v_fmac_f32_e32 v178, v11, v11
	v_fmac_f32_e32 v178, v250, v250
	v_fmac_f32_e32 v178, v12, v12
	v_fmac_f32_e32 v178, v251, v251
	v_fmac_f32_e32 v178, v13, v13
	v_fmac_f32_e32 v178, v176, v176
	v_fmac_f32_e32 v178, v14, v14
	v_fmac_f32_e32 v178, v177, v177
	v_fmac_f32_e32 v178, v15, v15
	s_waitcnt vmcnt(16)
	v_lshlrev_b32_e32 v238, 16, v16
	v_and_b32_e32 v16, 0xffff0000, v16
	v_add_f32_dpp v178, v178, v178 quad_perm:[1,0,3,2] row_mask:0xf bank_mask:0xf bound_ctrl:1
	v_lshlrev_b32_e32 v239, 16, v17
	v_and_b32_e32 v17, 0xffff0000, v17
	v_add_f32_dpp v178, v178, v178 quad_perm:[2,3,0,1] row_mask:0xf bank_mask:0xf bound_ctrl:1
	v_lshlrev_b32_e32 v240, 16, v18
	v_and_b32_e32 v18, 0xffff0000, v18
	v_add_f32_dpp v178, v178, v178 row_half_mirror row_mask:0xf bank_mask:0xf bound_ctrl:1
	v_lshlrev_b32_e32 v241, 16, v19
	v_and_b32_e32 v19, 0xffff0000, v19
	v_add_f32_dpp v178, v178, v178 row_mirror row_mask:0xf bank_mask:0xf bound_ctrl:1
	v_lshlrev_b32_e32 v242, 16, v20
	v_and_b32_e32 v20, 0xffff0000, v20
	v_add_f32_dpp v178, v178, v178 row_bcast:15 row_mask:0xa bank_mask:0xf
	v_lshlrev_b32_e32 v243, 16, v21
	v_and_b32_e32 v21, 0xffff0000, v21
	v_add_f32_dpp v178, v178, v178 row_bcast:31 row_mask:0xc bank_mask:0xf
	v_lshlrev_b32_e32 v244, 16, v22
	v_and_b32_e32 v22, 0xffff0000, v22
	v_lshlrev_b32_e32 v245, 16, v23
	v_and_b32_e32 v23, 0xffff0000, v23
	v_readlane_b32 s0, v178, 63
	s_nop 1
	v_mov_b32_e32 v181, s0
	v_fmamk_f32 v181, v181, 0x3a800000, v161
	v_rsq_f32_e32 v179, v181
	s_nop 0
	v_mul_f32_e32 v246, v246, v179
	v_mul_f32_e32 v8, v8, v179
	v_mul_f32_e32 v247, v247, v179
	v_mul_f32_e32 v9, v9, v179
	v_mul_f32_e32 v248, v248, v179
	v_mul_f32_e32 v10, v10, v179
	v_mul_f32_e32 v249, v249, v179
	v_mul_f32_e32 v11, v11, v179
	v_mul_f32_e32 v250, v250, v179
	v_mul_f32_e32 v12, v12, v179
	v_mul_f32_e32 v251, v251, v179
	v_mul_f32_e32 v13, v13, v179
	v_mul_f32_e32 v176, v176, v179
	v_mul_f32_e32 v14, v14, v179
	v_mul_f32_e32 v177, v177, v179
	v_mul_f32_e32 v15, v15, v179
	v_fmac_f32_e32 v238, v88, v246
	v_fmac_f32_e32 v16, v89, v8
	v_fmac_f32_e32 v239, v90, v247
	v_fmac_f32_e32 v17, v91, v9
	v_fmac_f32_e32 v240, v92, v248
	v_fmac_f32_e32 v18, v93, v10
	v_fmac_f32_e32 v241, v94, v249
	v_fmac_f32_e32 v19, v95, v11
	v_fmac_f32_e32 v242, v96, v250
	v_fmac_f32_e32 v20, v97, v12
	v_fmac_f32_e32 v243, v98, v251
	v_fmac_f32_e32 v21, v99, v13
	v_fmac_f32_e32 v244, v100, v176
	v_fmac_f32_e32 v22, v101, v14
	v_fmac_f32_e32 v245, v102, v177
	v_fmac_f32_e32 v23, v103, v15
	v_add_u32_e32 v181, 0x1000000, v1
	v_mov_b32_e32 v120, v238
	v_mov_b32_e32 v121, v16
	v_mov_b32_e32 v122, v239
	v_mov_b32_e32 v123, v17
	global_store_dwordx4 v181, v[120:123], s[10:11] offset:0
	v_mov_b32_e32 v124, v240
	v_mov_b32_e32 v125, v18
	v_mov_b32_e32 v126, v241
	v_mov_b32_e32 v127, v19
	global_store_dwordx4 v181, v[124:127], s[10:11] offset:1024
	v_mov_b32_e32 v150, v242
	v_mov_b32_e32 v151, v20
	v_mov_b32_e32 v152, v243
	v_mov_b32_e32 v153, v21
	global_store_dwordx4 v181, v[150:153], s[10:11] offset:2048
	v_mov_b32_e32 v154, v244
	v_mov_b32_e32 v155, v22
	v_mov_b32_e32 v156, v245
	v_mov_b32_e32 v157, v23
	global_store_dwordx4 v181, v[154:157], s[10:11] offset:3072
	s_waitcnt vmcnt(16)
	v_lshlrev_b32_e32 v246, 16, v190
	v_and_b32_e32 v190, 0xffff0000, v190
	v_lshlrev_b32_e32 v247, 16, v191
	v_and_b32_e32 v191, 0xffff0000, v191
	v_lshlrev_b32_e32 v248, 16, v192
	v_and_b32_e32 v192, 0xffff0000, v192
	v_lshlrev_b32_e32 v249, 16, v193
	v_and_b32_e32 v193, 0xffff0000, v193
	v_lshlrev_b32_e32 v250, 16, v194
	v_and_b32_e32 v194, 0xffff0000, v194
	v_lshlrev_b32_e32 v251, 16, v195
	v_and_b32_e32 v195, 0xffff0000, v195
	v_lshlrev_b32_e32 v176, 16, v196
	v_and_b32_e32 v196, 0xffff0000, v196
	v_lshlrev_b32_e32 v177, 16, v197
	v_and_b32_e32 v197, 0xffff0000, v197
	v_mul_f32_e32 v178, v246, v246
	v_fmac_f32_e32 v178, v190, v190
	v_fmac_f32_e32 v178, v247, v247
	v_fmac_f32_e32 v178, v191, v191
	v_fmac_f32_e32 v178, v248, v248
	v_fmac_f32_e32 v178, v192, v192
	v_fmac_f32_e32 v178, v249, v249
	v_fmac_f32_e32 v178, v193, v193
	v_fmac_f32_e32 v178, v250, v250
	v_fmac_f32_e32 v178, v194, v194
	v_fmac_f32_e32 v178, v251, v251
	v_fmac_f32_e32 v178, v195, v195
	v_fmac_f32_e32 v178, v176, v176
	v_fmac_f32_e32 v178, v196, v196
	v_fmac_f32_e32 v178, v177, v177
	v_fmac_f32_e32 v178, v197, v197
	s_waitcnt vmcnt(12)
	v_lshlrev_b32_e32 v238, 16, v198
	v_and_b32_e32 v198, 0xffff0000, v198
	v_add_f32_dpp v178, v178, v178 quad_perm:[1,0,3,2] row_mask:0xf bank_mask:0xf bound_ctrl:1
	v_lshlrev_b32_e32 v239, 16, v199
	v_and_b32_e32 v199, 0xffff0000, v199
	v_add_f32_dpp v178, v178, v178 quad_perm:[2,3,0,1] row_mask:0xf bank_mask:0xf bound_ctrl:1
	v_lshlrev_b32_e32 v240, 16, v200
	v_and_b32_e32 v200, 0xffff0000, v200
	v_add_f32_dpp v178, v178, v178 row_half_mirror row_mask:0xf bank_mask:0xf bound_ctrl:1
	v_lshlrev_b32_e32 v241, 16, v201
	v_and_b32_e32 v201, 0xffff0000, v201
	v_add_f32_dpp v178, v178, v178 row_mirror row_mask:0xf bank_mask:0xf bound_ctrl:1
	v_lshlrev_b32_e32 v242, 16, v202
	v_and_b32_e32 v202, 0xffff0000, v202
	v_add_f32_dpp v178, v178, v178 row_bcast:15 row_mask:0xa bank_mask:0xf
	v_lshlrev_b32_e32 v243, 16, v203
	v_and_b32_e32 v203, 0xffff0000, v203
	v_add_f32_dpp v178, v178, v178 row_bcast:31 row_mask:0xc bank_mask:0xf
	v_lshlrev_b32_e32 v244, 16, v204
	v_and_b32_e32 v204, 0xffff0000, v204
	v_lshlrev_b32_e32 v245, 16, v205
	v_and_b32_e32 v205, 0xffff0000, v205
	v_readlane_b32 s0, v178, 63
	s_nop 1
	v_mov_b32_e32 v181, s0
	v_fmamk_f32 v181, v181, 0x3a800000, v161
	v_rsq_f32_e32 v179, v181
	s_nop 0
	v_mul_f32_e32 v246, v246, v179
	v_mul_f32_e32 v190, v190, v179
	v_mul_f32_e32 v247, v247, v179
	v_mul_f32_e32 v191, v191, v179
	v_mul_f32_e32 v248, v248, v179
	v_mul_f32_e32 v192, v192, v179
	v_mul_f32_e32 v249, v249, v179
	v_mul_f32_e32 v193, v193, v179
	v_mul_f32_e32 v250, v250, v179
	v_mul_f32_e32 v194, v194, v179
	v_mul_f32_e32 v251, v251, v179
	v_mul_f32_e32 v195, v195, v179
	v_mul_f32_e32 v176, v176, v179
	v_mul_f32_e32 v196, v196, v179
	v_mul_f32_e32 v177, v177, v179
	v_mul_f32_e32 v197, v197, v179
	v_fmac_f32_e32 v238, v88, v246
	v_fmac_f32_e32 v198, v89, v190
	v_fmac_f32_e32 v239, v90, v247
	v_fmac_f32_e32 v199, v91, v191
	v_fmac_f32_e32 v240, v92, v248
	v_fmac_f32_e32 v200, v93, v192
	v_fmac_f32_e32 v241, v94, v249
	v_fmac_f32_e32 v201, v95, v193
	v_fmac_f32_e32 v242, v96, v250
	v_fmac_f32_e32 v202, v97, v194
	v_fmac_f32_e32 v243, v98, v251
	v_fmac_f32_e32 v203, v99, v195
	v_fmac_f32_e32 v244, v100, v176
	v_fmac_f32_e32 v204, v101, v196
	v_fmac_f32_e32 v245, v102, v177
	v_fmac_f32_e32 v205, v103, v197
	v_add_u32_e32 v181, 0x1800000, v1
	v_mov_b32_e32 v120, v238
	v_mov_b32_e32 v121, v198
	v_mov_b32_e32 v122, v239
	v_mov_b32_e32 v123, v199
	global_store_dwordx4 v181, v[120:123], s[10:11] offset:0
	v_mov_b32_e32 v124, v240
	v_mov_b32_e32 v125, v200
	v_mov_b32_e32 v126, v241
	v_mov_b32_e32 v127, v201
	global_store_dwordx4 v181, v[124:127], s[10:11] offset:1024
	v_mov_b32_e32 v150, v242
	v_mov_b32_e32 v151, v202
	v_mov_b32_e32 v152, v243
	v_mov_b32_e32 v153, v203
	global_store_dwordx4 v181, v[150:153], s[10:11] offset:2048
	v_mov_b32_e32 v154, v244
	v_mov_b32_e32 v155, v204
	v_mov_b32_e32 v156, v245
	v_mov_b32_e32 v157, v205
	global_store_dwordx4 v181, v[154:157], s[10:11] offset:3072
	s_branch .LBB0_100

.LBB0_168:
	s_andn2_b64 vcc, exec, s[4:5]
	s_cbranch_vccnz .LBB0_213
	v_readlane_b32 s0, v254, 40
	s_cmp_gt_i32 s0, 4
	s_mov_b64 s[0:1], -1
	s_cbranch_scc0 .LBB0_190
	v_readfirstlane_b32 s0, v160
	v_readlane_b32 s1, v252, 7
	s_lshr_b32 s0, s0, 6
	s_mov_b32 s73, s0
	s_add_i32 s0, s0, s1
	v_readlane_b32 s62, v254, 34
	s_sub_u32 s64, s78, 0x110
	s_subb_u32 s65, s79, 0
	s_load_dwordx2 s[66:67], s[64:65], 0x40
	s_load_dwordx2 s[10:11], s[64:65], 0xf8
	s_lshl_b32 s63, s0, 11
	s_add_u32 s4, s84, 0x167ca000
	s_addc_u32 s5, s85, 0
	s_add_u32 s4, s4, s63
	s_addc_u32 s5, s5, 0
	s_add_u32 s6, s84, 0x112ca000
	s_addc_u32 s7, s85, 0
	s_add_u32 s6, s6, s63
	s_addc_u32 s7, s7, 0
	v_and_b32_e32 v0, 63, v160
	v_lshlrev_b32_e32 v1, 4, v0
	v_lshlrev_b32_e32 v0, 3, v0
	v_add_u32_e32 v2, 0x400000, v0
	v_add_u32_e32 v3, 0x800000, v0
	v_add_u32_e32 v4, 0xc00000, v0
	v_add_u32_e32 v5, 0x1000000, v0
	global_load_dwordx2 v[8:9], v5, s[6:7] offset:0 nt
	global_load_dwordx2 v[10:11], v5, s[6:7] offset:512 nt
	global_load_dwordx2 v[12:13], v5, s[6:7] offset:1024 nt
	global_load_dwordx2 v[14:15], v5, s[6:7] offset:1536 nt
	global_load_dwordx2 v[16:17], v5, s[4:5] offset:0 nt
	global_load_dwordx2 v[18:19], v5, s[4:5] offset:512 nt
	global_load_dwordx2 v[20:21], v5, s[4:5] offset:1024 nt
	global_load_dwordx2 v[22:23], v5, s[4:5] offset:1536 nt
	s_add_u32 s8, s84, 0xaeca000
	s_addc_u32 s9, s85, 0
	s_add_u32 s8, s8, s63
	s_addc_u32 s9, s9, 0
	s_lshr_b32 s69, s0, 10
	s_add_i32 s69, s69, 1
	s_mul_i32 s69, s69, 0x6000
	s_mul_i32 s68, s62, 0x12000
	s_lshl_b32 s72, s62, 14
	s_add_i32 s70, s72, 0x2000
	s_add_i32 s72, s72, 0x1000
	s_add_u32 s16, s84, 0x6602000
	s_addc_u32 s17, s85, 0
	s_add_u32 s16, s16, s68
	s_addc_u32 s17, s17, 0
	s_add_u32 s20, s16, 0x1000
	s_addc_u32 s21, s17, 0
	s_add_u32 s18, s16, 0x2000
	s_addc_u32 s19, s17, 0
	s_add_u32 s22, s16, s69
	s_addc_u32 s23, s17, 0
	s_add_u32 s60, s20, s69
	s_addc_u32 s61, s21, 0
	s_add_u32 s26, s18, s69
	s_addc_u32 s27, s19, 0
	s_lshl_b32 s63, s63, 1
	s_waitcnt lgkmcnt(0)
	s_add_u32 s12, s66, s72
	s_addc_u32 s13, s67, 0
	s_add_u32 s14, s66, s70
	s_addc_u32 s15, s67, 0
	s_add_u32 s10, s10, s63
	s_addc_u32 s11, s11, 0
	s_mov_b64 s[74:75], s[12:13]
	s_cmp_eq_u32 s73, 1
	s_cselect_b32 s74, s14, s74
	s_cselect_b32 s75, s15, s75
	s_cmp_eq_u32 s73, 2
	s_cselect_b32 s74, s16, s74
	s_cselect_b32 s75, s17, s75
	s_cmp_eq_u32 s73, 3
	s_cselect_b32 s74, s18, s74
	s_cselect_b32 s75, s19, s75
	s_cmp_eq_u32 s73, 4
	s_cselect_b32 s74, s20, s74
	s_cselect_b32 s75, s21, s75
	s_cmp_eq_u32 s73, 5
	s_cselect_b32 s74, s22, s74
	s_cselect_b32 s75, s23, s75
	s_cmp_eq_u32 s73, 6
	s_cselect_b32 s74, s26, s74
	s_cselect_b32 s75, s27, s75
	s_cmp_eq_u32 s73, 7
	s_cselect_b32 s74, s60, s74
	s_cselect_b32 s75, s61, s75
	global_load_dwordx4 v[222:225], v1, s[74:75] offset:0
	global_load_dwordx4 v[226:229], v1, s[74:75] offset:1024
	global_load_dwordx4 v[230:233], v1, s[74:75] offset:2048
	global_load_dwordx4 v[234:237], v1, s[74:75] offset:3072
	s_lshl_b32 s74, s73, 12
	v_add_u32_e32 v6, s74, v1
	global_load_dwordx2 v[24:25], v0, s[6:7] offset:0 nt
	global_load_dwordx2 v[26:27], v0, s[6:7] offset:512 nt
	global_load_dwordx2 v[28:29], v0, s[6:7] offset:1024 nt
	global_load_dwordx2 v[30:31], v0, s[6:7] offset:1536 nt
	global_load_dwordx2 v[32:33], v0, s[4:5] offset:0 nt
	global_load_dwordx2 v[34:35], v0, s[4:5] offset:512 nt
	global_load_dwordx2 v[36:37], v0, s[4:5] offset:1024 nt
	global_load_dwordx2 v[38:39], v0, s[4:5] offset:1536 nt
	global_load_dwordx2 v[40:41], v2, s[6:7] offset:0 nt
	global_load_dwordx2 v[42:43], v2, s[6:7] offset:512 nt
	global_load_dwordx2 v[44:45], v2, s[6:7] offset:1024 nt
	global_load_dwordx2 v[46:47], v2, s[6:7] offset:1536 nt
	global_load_dwordx2 v[48:49], v2, s[4:5] offset:0 nt
	global_load_dwordx2 v[50:51], v2, s[4:5] offset:512 nt
	global_load_dwordx2 v[52:53], v2, s[4:5] offset:1024 nt
	global_load_dwordx2 v[54:55], v2, s[4:5] offset:1536 nt
	s_waitcnt vmcnt(16)
	ds_write_b128 v6, v[222:225] offset:0
	ds_write_b128 v6, v[226:229] offset:1024
	ds_write_b128 v6, v[230:233] offset:2048
	ds_write_b128 v6, v[234:237] offset:3072
	s_waitcnt lgkmcnt(0)
	s_barrier
	ds_read_b128 v[56:59], v1 offset:0
	ds_read_b128 v[60:63], v1 offset:1024
	ds_read_b128 v[64:67], v1 offset:2048
	ds_read_b128 v[68:71], v1 offset:3072
	ds_read_b128 v[72:75], v1 offset:4096
	ds_read_b128 v[76:79], v1 offset:5120
	ds_read_b128 v[80:83], v1 offset:6144
	ds_read_b128 v[84:87], v1 offset:7168
	ds_read_b128 v[88:91], v1 offset:8192
	ds_read_b128 v[92:95], v1 offset:9216
	ds_read_b128 v[96:99], v1 offset:10240
	ds_read_b128 v[100:103], v1 offset:11264
	ds_read_b128 v[104:107], v1 offset:12288
	ds_read_b128 v[108:111], v1 offset:13312
	ds_read_b128 v[112:115], v1 offset:14336
	ds_read_b128 v[116:119], v1 offset:15360
	ds_read_b128 v[134:137], v1 offset:16384
	ds_read_b128 v[138:141], v1 offset:17408
	ds_read_b128 v[142:145], v1 offset:18432
	ds_read_b128 v[146:149], v1 offset:19456
	ds_read_b128 v[190:193], v1 offset:20480
	ds_read_b128 v[194:197], v1 offset:21504
	ds_read_b128 v[198:201], v1 offset:22528
	ds_read_b128 v[202:205], v1 offset:23552
	ds_read_b128 v[206:209], v1 offset:24576
	ds_read_b128 v[210:213], v1 offset:25600
	ds_read_b128 v[214:217], v1 offset:26624
	ds_read_b128 v[218:221], v1 offset:27648
	ds_read_b128 v[222:225], v1 offset:28672
	ds_read_b128 v[226:229], v1 offset:29696
	ds_read_b128 v[230:233], v1 offset:30720
	ds_read_b128 v[234:237], v1 offset:31744
	s_waitcnt lgkmcnt(0)
	v_mul_f32_e32 v190, v190, v56
	v_mul_f32_e32 v191, v191, v57
	v_mul_f32_e32 v192, v192, v58
	v_mul_f32_e32 v193, v193, v59
	v_mul_f32_e32 v194, v194, v60
	v_mul_f32_e32 v195, v195, v61
	v_mul_f32_e32 v196, v196, v62
	v_mul_f32_e32 v197, v197, v63
	v_mul_f32_e32 v198, v198, v64
	v_mul_f32_e32 v199, v199, v65
	v_mul_f32_e32 v200, v200, v66
	v_mul_f32_e32 v201, v201, v67
	v_mul_f32_e32 v202, v202, v68
	v_mul_f32_e32 v203, v203, v69
	v_mul_f32_e32 v204, v204, v70
	v_mul_f32_e32 v205, v205, v71
	v_mul_f32_e32 v88, v88, v56
	v_mul_f32_e32 v89, v89, v57
	v_mul_f32_e32 v90, v90, v58
	v_mul_f32_e32 v91, v91, v59
	v_mul_f32_e32 v92, v92, v60
	v_mul_f32_e32 v93, v93, v61
	v_mul_f32_e32 v94, v94, v62
	v_mul_f32_e32 v95, v95, v63
	v_mul_f32_e32 v96, v96, v64
	v_mul_f32_e32 v97, v97, v65
	v_mul_f32_e32 v98, v98, v66
	v_mul_f32_e32 v99, v99, v67
	v_mul_f32_e32 v100, v100, v68
	v_mul_f32_e32 v101, v101, v69
	v_mul_f32_e32 v102, v102, v70
	v_mul_f32_e32 v103, v103, v71
	v_add_f32_e32 v206, 1.0, v206
	v_add_f32_e32 v207, 1.0, v207
	v_add_f32_e32 v208, 1.0, v208
	v_add_f32_e32 v209, 1.0, v209
	v_add_f32_e32 v210, 1.0, v210
	v_add_f32_e32 v211, 1.0, v211
	v_add_f32_e32 v212, 1.0, v212
	v_add_f32_e32 v213, 1.0, v213
	v_add_f32_e32 v214, 1.0, v214
	v_add_f32_e32 v215, 1.0, v215
	v_add_f32_e32 v216, 1.0, v216
	v_add_f32_e32 v217, 1.0, v217
	v_add_f32_e32 v218, 1.0, v218
	v_add_f32_e32 v219, 1.0, v219
	v_add_f32_e32 v220, 1.0, v220
	v_add_f32_e32 v221, 1.0, v221
	v_mul_f32_e32 v206, v206, v72
	v_mul_f32_e32 v207, v207, v73
	v_mul_f32_e32 v208, v208, v74
	v_mul_f32_e32 v209, v209, v75
	v_mul_f32_e32 v210, v210, v76
	v_mul_f32_e32 v211, v211, v77
	v_mul_f32_e32 v212, v212, v78
	v_mul_f32_e32 v213, v213, v79
	v_mul_f32_e32 v214, v214, v80
	v_mul_f32_e32 v215, v215, v81
	v_mul_f32_e32 v216, v216, v82
	v_mul_f32_e32 v217, v217, v83
	v_mul_f32_e32 v218, v218, v84
	v_mul_f32_e32 v219, v219, v85
	v_mul_f32_e32 v220, v220, v86
	v_mul_f32_e32 v221, v221, v87
	v_add_f32_e32 v104, 1.0, v104
	v_add_f32_e32 v105, 1.0, v105
	v_add_f32_e32 v106, 1.0, v106
	v_add_f32_e32 v107, 1.0, v107
	v_add_f32_e32 v108, 1.0, v108
	v_add_f32_e32 v109, 1.0, v109
	v_add_f32_e32 v110, 1.0, v110
	v_add_f32_e32 v111, 1.0, v111
	v_add_f32_e32 v112, 1.0, v112
	v_add_f32_e32 v113, 1.0, v113
	v_add_f32_e32 v114, 1.0, v114
	v_add_f32_e32 v115, 1.0, v115
	v_add_f32_e32 v116, 1.0, v116
	v_add_f32_e32 v117, 1.0, v117
	v_add_f32_e32 v118, 1.0, v118
	v_add_f32_e32 v119, 1.0, v119
	v_mul_f32_e32 v104, v104, v72
	v_mul_f32_e32 v105, v105, v73
	v_mul_f32_e32 v106, v106, v74
	v_mul_f32_e32 v107, v107, v75
	v_mul_f32_e32 v108, v108, v76
	v_mul_f32_e32 v109, v109, v77
	v_mul_f32_e32 v110, v110, v78
	v_mul_f32_e32 v111, v111, v79
	v_mul_f32_e32 v112, v112, v80
	v_mul_f32_e32 v113, v113, v81
	v_mul_f32_e32 v114, v114, v82
	v_mul_f32_e32 v115, v115, v83
	v_mul_f32_e32 v116, v116, v84
	v_mul_f32_e32 v117, v117, v85
	v_mul_f32_e32 v118, v118, v86
	v_mul_f32_e32 v119, v119, v87
	v_lshlrev_b32_e32 v246, 16, v8
	v_and_b32_e32 v8, 0xffff0000, v8
	v_lshlrev_b32_e32 v247, 16, v9
	v_and_b32_e32 v9, 0xffff0000, v9
	v_lshlrev_b32_e32 v248, 16, v10
	v_and_b32_e32 v10, 0xffff0000, v10
	v_lshlrev_b32_e32 v249, 16, v11
	v_and_b32_e32 v11, 0xffff0000, v11
	v_lshlrev_b32_e32 v250, 16, v12
	v_and_b32_e32 v12, 0xffff0000, v12
	v_lshlrev_b32_e32 v251, 16, v13
	v_and_b32_e32 v13, 0xffff0000, v13
	v_lshlrev_b32_e32 v176, 16, v14
	v_and_b32_e32 v14, 0xffff0000, v14
	v_lshlrev_b32_e32 v177, 16, v15
	v_and_b32_e32 v15, 0xffff0000, v15
	v_mul_f32_e32 v178, v246, v246
	v_fmac_f32_e32 v178, v8, v8
	v_fmac_f32_e32 v178, v247, v247
	v_fmac_f32_e32 v178, v9, v9
	v_fmac_f32_e32 v178, v248, v248
	v_fmac_f32_e32 v178, v10, v10
	v_fmac_f32_e32 v178, v249, v249
	v_fmac_f32_e32 v178, v11, v11
	v_fmac_f32_e32 v178, v250, v250
	v_fmac_f32_e32 v178, v12, v12
	v_fmac_f32_e32 v178, v251, v251
	v_fmac_f32_e32 v178, v13, v13
	v_fmac_f32_e32 v178, v176, v176
	v_fmac_f32_e32 v178, v14, v14
	v_fmac_f32_e32 v178, v177, v177
	v_fmac_f32_e32 v178, v15, v15
	v_lshlrev_b32_e32 v238, 16, v16
	v_and_b32_e32 v16, 0xffff0000, v16
	v_add_f32_dpp v178, v178, v178 quad_perm:[1,0,3,2] row_mask:0xf bank_mask:0xf bound_ctrl:1
	v_lshlrev_b32_e32 v239, 16, v17
	v_and_b32_e32 v17, 0xffff0000, v17
	v_add_f32_dpp v178, v178, v178 quad_perm:[2,3,0,1] row_mask:0xf bank_mask:0xf bound_ctrl:1
	v_lshlrev_b32_e32 v240, 16, v18
	v_and_b32_e32 v18, 0xffff0000, v18
	v_add_f32_dpp v178, v178, v178 row_half_mirror row_mask:0xf bank_mask:0xf bound_ctrl:1
	v_lshlrev_b32_e32 v241, 16, v19
	v_and_b32_e32 v19, 0xffff0000, v19
	v_add_f32_dpp v178, v178, v178 row_mirror row_mask:0xf bank_mask:0xf bound_ctrl:1
	v_lshlrev_b32_e32 v242, 16, v20
	v_and_b32_e32 v20, 0xffff0000, v20
	v_add_f32_dpp v178, v178, v178 row_bcast:15 row_mask:0xa bank_mask:0xf
	v_lshlrev_b32_e32 v243, 16, v21
	v_and_b32_e32 v21, 0xffff0000, v21
	v_add_f32_dpp v178, v178, v178 row_bcast:31 row_mask:0xc bank_mask:0xf
	v_lshlrev_b32_e32 v244, 16, v22
	v_and_b32_e32 v22, 0xffff0000, v22
	v_lshlrev_b32_e32 v245, 16, v23
	v_and_b32_e32 v23, 0xffff0000, v23
	v_readlane_b32 s0, v178, 63
	s_nop 1
	v_mov_b32_e32 v181, s0
	v_fmamk_f32 v181, v181, 0x3a800000, v161
	v_rsq_f32_e32 v179, v181
	s_nop 0
	s_waitcnt lgkmcnt(0)
	v_mul_f32_e32 v246, v246, v179
	v_mul_f32_e32 v8, v8, v179
	v_mul_f32_e32 v247, v247, v179
	v_mul_f32_e32 v9, v9, v179
	v_mul_f32_e32 v248, v248, v179
	v_mul_f32_e32 v10, v10, v179
	v_mul_f32_e32 v249, v249, v179
	v_mul_f32_e32 v11, v11, v179
	v_mul_f32_e32 v250, v250, v179
	v_mul_f32_e32 v12, v12, v179
	v_mul_f32_e32 v251, v251, v179
	v_mul_f32_e32 v13, v13, v179
	v_mul_f32_e32 v176, v176, v179
	v_mul_f32_e32 v14, v14, v179
	v_mul_f32_e32 v177, v177, v179
	v_mul_f32_e32 v15, v15, v179
	v_fmac_f32_e32 v238, v190, v246
	v_fmac_f32_e32 v16, v191, v8
	v_fmac_f32_e32 v239, v192, v247
	v_fmac_f32_e32 v17, v193, v9
	v_fmac_f32_e32 v240, v194, v248
	v_fmac_f32_e32 v18, v195, v10
	v_fmac_f32_e32 v241, v196, v249
	v_fmac_f32_e32 v19, v197, v11
	v_fmac_f32_e32 v242, v198, v250
	v_fmac_f32_e32 v20, v199, v12
	v_fmac_f32_e32 v243, v200, v251
	v_fmac_f32_e32 v21, v201, v13
	v_fmac_f32_e32 v244, v202, v176
	v_fmac_f32_e32 v22, v203, v14
	v_fmac_f32_e32 v245, v204, v177
	v_fmac_f32_e32 v23, v205, v15
	v_cvt_pk_bf16_f32 v120, v238, v16
	v_cvt_pk_bf16_f32 v121, v239, v17
	global_store_dwordx2 v5, v[120:121], s[4:5] offset:0 nt
	v_cvt_pk_bf16_f32 v122, v240, v18
	v_cvt_pk_bf16_f32 v123, v241, v19
	global_store_dwordx2 v5, v[122:123], s[4:5] offset:512 nt
	v_cvt_pk_bf16_f32 v124, v242, v20
	v_cvt_pk_bf16_f32 v125, v243, v21
	global_store_dwordx2 v5, v[124:125], s[4:5] offset:1024 nt
	v_cvt_pk_bf16_f32 v126, v244, v22
	v_cvt_pk_bf16_f32 v127, v245, v23
	global_store_dwordx2 v5, v[126:127], s[4:5] offset:1536 nt
	v_mul_f32_e32 v178, v238, v238
	v_fmac_f32_e32 v178, v16, v16
	v_fmac_f32_e32 v178, v239, v239
	v_fmac_f32_e32 v178, v17, v17
	v_fmac_f32_e32 v178, v240, v240
	v_fmac_f32_e32 v178, v18, v18
	v_fmac_f32_e32 v178, v241, v241
	v_fmac_f32_e32 v178, v19, v19
	v_fmac_f32_e32 v178, v242, v242
	v_fmac_f32_e32 v178, v20, v20
	v_fmac_f32_e32 v178, v243, v243
	v_fmac_f32_e32 v178, v21, v21
	v_fmac_f32_e32 v178, v244, v244
	v_fmac_f32_e32 v178, v22, v22
	v_fmac_f32_e32 v178, v245, v245
	v_fmac_f32_e32 v178, v23, v23
	s_nop 1
	v_add_f32_dpp v178, v178, v178 quad_perm:[1,0,3,2] row_mask:0xf bank_mask:0xf bound_ctrl:1
	s_nop 1
	v_add_f32_dpp v178, v178, v178 quad_perm:[2,3,0,1] row_mask:0xf bank_mask:0xf bound_ctrl:1
	s_nop 1
	v_add_f32_dpp v178, v178, v178 row_half_mirror row_mask:0xf bank_mask:0xf bound_ctrl:1
	s_nop 1
	v_add_f32_dpp v178, v178, v178 row_mirror row_mask:0xf bank_mask:0xf bound_ctrl:1
	s_nop 1
	v_add_f32_dpp v178, v178, v178 row_bcast:15 row_mask:0xa bank_mask:0xf
	s_nop 1
	v_add_f32_dpp v178, v178, v178 row_bcast:31 row_mask:0xc bank_mask:0xf
	s_nop 0
	v_readlane_b32 s0, v178, 63
	s_nop 1
	v_mov_b32_e32 v181, s0
	v_fmamk_f32 v181, v181, 0x3a800000, v161
	v_rsq_f32_e32 v180, v181
	s_nop 0
	v_mul_f32_e32 v238, v238, v180
	v_mul_f32_e32 v16, v16, v180
	v_mul_f32_e32 v239, v239, v180
	v_mul_f32_e32 v17, v17, v180
	v_mul_f32_e32 v240, v240, v180
	v_mul_f32_e32 v18, v18, v180
	v_mul_f32_e32 v241, v241, v180
	v_mul_f32_e32 v19, v19, v180
	v_mul_f32_e32 v242, v242, v180
	v_mul_f32_e32 v20, v20, v180
	v_mul_f32_e32 v243, v243, v180
	v_mul_f32_e32 v21, v21, v180
	v_mul_f32_e32 v244, v244, v180
	v_mul_f32_e32 v22, v22, v180
	v_mul_f32_e32 v245, v245, v180
	v_mul_f32_e32 v23, v23, v180
	v_fma_f32 v238, v238, v206, v222
	v_fma_f32 v16, v16, v207, v223
	v_fma_f32 v239, v239, v208, v224
	v_fma_f32 v17, v17, v209, v225
	v_fma_f32 v240, v240, v210, v226
	v_fma_f32 v18, v18, v211, v227
	v_fma_f32 v241, v241, v212, v228
	v_fma_f32 v19, v19, v213, v229
	v_fma_f32 v242, v242, v214, v230
	v_fma_f32 v20, v20, v215, v231
	v_fma_f32 v243, v243, v216, v232
	v_fma_f32 v21, v21, v217, v233
	v_fma_f32 v244, v244, v218, v234
	v_fma_f32 v22, v22, v219, v235
	v_fma_f32 v245, v245, v220, v236
	v_fma_f32 v23, v23, v221, v237
	v_cvt_pk_bf16_f32 v150, v238, v16
	v_cvt_pk_bf16_f32 v151, v239, v17
	global_store_dwordx2 v5, v[150:151], s[8:9] offset:0
	v_cvt_pk_bf16_f32 v152, v240, v18
	v_cvt_pk_bf16_f32 v153, v241, v19
	global_store_dwordx2 v5, v[152:153], s[8:9] offset:512
	v_cvt_pk_bf16_f32 v154, v242, v20
	v_cvt_pk_bf16_f32 v155, v243, v21
	global_store_dwordx2 v5, v[154:155], s[8:9] offset:1024
	v_cvt_pk_bf16_f32 v156, v244, v22
	v_cvt_pk_bf16_f32 v157, v245, v23
	global_store_dwordx2 v5, v[156:157], s[8:9] offset:1536
	global_load_dwordx2 v[8:9], v3, s[6:7] offset:0 nt
	global_load_dwordx2 v[10:11], v3, s[6:7] offset:512 nt
	global_load_dwordx2 v[12:13], v3, s[6:7] offset:1024 nt
	global_load_dwordx2 v[14:15], v3, s[6:7] offset:1536 nt
	global_load_dwordx2 v[16:17], v3, s[4:5] offset:0 nt
	global_load_dwordx2 v[18:19], v3, s[4:5] offset:512 nt
	global_load_dwordx2 v[20:21], v3, s[4:5] offset:1024 nt
	global_load_dwordx2 v[22:23], v3, s[4:5] offset:1536 nt
	global_load_dwordx2 v[190:191], v4, s[6:7] offset:0 nt
	global_load_dwordx2 v[192:193], v4, s[6:7] offset:512 nt
	global_load_dwordx2 v[194:195], v4, s[6:7] offset:1024 nt
	global_load_dwordx2 v[196:197], v4, s[6:7] offset:1536 nt
	global_load_dwordx2 v[198:199], v4, s[4:5] offset:0 nt
	global_load_dwordx2 v[200:201], v4, s[4:5] offset:512 nt
	global_load_dwordx2 v[202:203], v4, s[4:5] offset:1024 nt
	global_load_dwordx2 v[204:205], v4, s[4:5] offset:1536 nt
	s_waitcnt vmcnt(36)
	v_lshlrev_b32_e32 v246, 16, v24
	v_and_b32_e32 v24, 0xffff0000, v24
	v_lshlrev_b32_e32 v247, 16, v25
	v_and_b32_e32 v25, 0xffff0000, v25
	v_lshlrev_b32_e32 v248, 16, v26
	v_and_b32_e32 v26, 0xffff0000, v26
	v_lshlrev_b32_e32 v249, 16, v27
	v_and_b32_e32 v27, 0xffff0000, v27
	v_lshlrev_b32_e32 v250, 16, v28
	v_and_b32_e32 v28, 0xffff0000, v28
	v_lshlrev_b32_e32 v251, 16, v29
	v_and_b32_e32 v29, 0xffff0000, v29
	v_lshlrev_b32_e32 v176, 16, v30
	v_and_b32_e32 v30, 0xffff0000, v30
	v_lshlrev_b32_e32 v177, 16, v31
	v_and_b32_e32 v31, 0xffff0000, v31
	v_mul_f32_e32 v178, v246, v246
	v_fmac_f32_e32 v178, v24, v24
	v_fmac_f32_e32 v178, v247, v247
	v_fmac_f32_e32 v178, v25, v25
	v_fmac_f32_e32 v178, v248, v248
	v_fmac_f32_e32 v178, v26, v26
	v_fmac_f32_e32 v178, v249, v249
	v_fmac_f32_e32 v178, v27, v27
	v_fmac_f32_e32 v178, v250, v250
	v_fmac_f32_e32 v178, v28, v28
	v_fmac_f32_e32 v178, v251, v251
	v_fmac_f32_e32 v178, v29, v29
	v_fmac_f32_e32 v178, v176, v176
	v_fmac_f32_e32 v178, v30, v30
	v_fmac_f32_e32 v178, v177, v177
	v_fmac_f32_e32 v178, v31, v31
	s_waitcnt vmcnt(32)
	v_lshlrev_b32_e32 v238, 16, v32
	v_and_b32_e32 v32, 0xffff0000, v32
	v_add_f32_dpp v178, v178, v178 quad_perm:[1,0,3,2] row_mask:0xf bank_mask:0xf bound_ctrl:1
	v_lshlrev_b32_e32 v239, 16, v33
	v_and_b32_e32 v33, 0xffff0000, v33
	v_add_f32_dpp v178, v178, v178 quad_perm:[2,3,0,1] row_mask:0xf bank_mask:0xf bound_ctrl:1
	v_lshlrev_b32_e32 v240, 16, v34
	v_and_b32_e32 v34, 0xffff0000, v34
	v_add_f32_dpp v178, v178, v178 row_half_mirror row_mask:0xf bank_mask:0xf bound_ctrl:1
	v_lshlrev_b32_e32 v241, 16, v35
	v_and_b32_e32 v35, 0xffff0000, v35
	v_add_f32_dpp v178, v178, v178 row_mirror row_mask:0xf bank_mask:0xf bound_ctrl:1
	v_lshlrev_b32_e32 v242, 16, v36
	v_and_b32_e32 v36, 0xffff0000, v36
	v_add_f32_dpp v178, v178, v178 row_bcast:15 row_mask:0xa bank_mask:0xf
	v_lshlrev_b32_e32 v243, 16, v37
	v_and_b32_e32 v37, 0xffff0000, v37
	v_add_f32_dpp v178, v178, v178 row_bcast:31 row_mask:0xc bank_mask:0xf
	v_lshlrev_b32_e32 v244, 16, v38
	v_and_b32_e32 v38, 0xffff0000, v38
	v_lshlrev_b32_e32 v245, 16, v39
	v_and_b32_e32 v39, 0xffff0000, v39
	v_readlane_b32 s0, v178, 63
	s_nop 1
	v_mov_b32_e32 v181, s0
	v_fmamk_f32 v181, v181, 0x3a800000, v161
	v_rsq_f32_e32 v179, v181
	s_nop 0
	v_mul_f32_e32 v246, v246, v179
	v_mul_f32_e32 v24, v24, v179
	v_mul_f32_e32 v247, v247, v179
	v_mul_f32_e32 v25, v25, v179
	v_mul_f32_e32 v248, v248, v179
	v_mul_f32_e32 v26, v26, v179
	v_mul_f32_e32 v249, v249, v179
	v_mul_f32_e32 v27, v27, v179
	v_mul_f32_e32 v250, v250, v179
	v_mul_f32_e32 v28, v28, v179
	v_mul_f32_e32 v251, v251, v179
	v_mul_f32_e32 v29, v29, v179
	v_mul_f32_e32 v176, v176, v179
	v_mul_f32_e32 v30, v30, v179
	v_mul_f32_e32 v177, v177, v179
	v_mul_f32_e32 v31, v31, v179
	v_fmac_f32_e32 v238, v88, v246
	v_fmac_f32_e32 v32, v89, v24
	v_fmac_f32_e32 v239, v90, v247
	v_fmac_f32_e32 v33, v91, v25
	v_fmac_f32_e32 v240, v92, v248
	v_fmac_f32_e32 v34, v93, v26
	v_fmac_f32_e32 v241, v94, v249
	v_fmac_f32_e32 v35, v95, v27
	v_fmac_f32_e32 v242, v96, v250
	v_fmac_f32_e32 v36, v97, v28
	v_fmac_f32_e32 v243, v98, v251
	v_fmac_f32_e32 v37, v99, v29
	v_fmac_f32_e32 v244, v100, v176
	v_fmac_f32_e32 v38, v101, v30
	v_fmac_f32_e32 v245, v102, v177
	v_fmac_f32_e32 v39, v103, v31
	v_cvt_pk_bf16_f32 v120, v238, v32
	v_cvt_pk_bf16_f32 v121, v239, v33
	global_store_dwordx2 v0, v[120:121], s[4:5] offset:0 nt
	v_cvt_pk_bf16_f32 v122, v240, v34
	v_cvt_pk_bf16_f32 v123, v241, v35
	global_store_dwordx2 v0, v[122:123], s[4:5] offset:512 nt
	v_cvt_pk_bf16_f32 v124, v242, v36
	v_cvt_pk_bf16_f32 v125, v243, v37
	global_store_dwordx2 v0, v[124:125], s[4:5] offset:1024 nt
	v_cvt_pk_bf16_f32 v126, v244, v38
	v_cvt_pk_bf16_f32 v127, v245, v39
	global_store_dwordx2 v0, v[126:127], s[4:5] offset:1536 nt
	v_mul_f32_e32 v178, v238, v238
	v_fmac_f32_e32 v178, v32, v32
	v_fmac_f32_e32 v178, v239, v239
	v_fmac_f32_e32 v178, v33, v33
	v_fmac_f32_e32 v178, v240, v240
	v_fmac_f32_e32 v178, v34, v34
	v_fmac_f32_e32 v178, v241, v241
	v_fmac_f32_e32 v178, v35, v35
	v_fmac_f32_e32 v178, v242, v242
	v_fmac_f32_e32 v178, v36, v36
	v_fmac_f32_e32 v178, v243, v243
	v_fmac_f32_e32 v178, v37, v37
	v_fmac_f32_e32 v178, v244, v244
	v_fmac_f32_e32 v178, v38, v38
	v_fmac_f32_e32 v178, v245, v245
	v_fmac_f32_e32 v178, v39, v39
	s_nop 1
	v_add_f32_dpp v178, v178, v178 quad_perm:[1,0,3,2] row_mask:0xf bank_mask:0xf bound_ctrl:1
	s_nop 1
	v_add_f32_dpp v178, v178, v178 quad_perm:[2,3,0,1] row_mask:0xf bank_mask:0xf bound_ctrl:1
	s_nop 1
	v_add_f32_dpp v178, v178, v178 row_half_mirror row_mask:0xf bank_mask:0xf bound_ctrl:1
	s_nop 1
	v_add_f32_dpp v178, v178, v178 row_mirror row_mask:0xf bank_mask:0xf bound_ctrl:1
	s_nop 1
	v_add_f32_dpp v178, v178, v178 row_bcast:15 row_mask:0xa bank_mask:0xf
	s_nop 1
	v_add_f32_dpp v178, v178, v178 row_bcast:31 row_mask:0xc bank_mask:0xf
	s_nop 0
	v_readlane_b32 s0, v178, 63
	s_nop 1
	v_mov_b32_e32 v181, s0
	v_fmamk_f32 v181, v181, 0x3a800000, v161
	v_rsq_f32_e32 v180, v181
	s_nop 0
	v_mul_f32_e32 v238, v238, v180
	v_mul_f32_e32 v32, v32, v180
	v_mul_f32_e32 v239, v239, v180
	v_mul_f32_e32 v33, v33, v180
	v_mul_f32_e32 v240, v240, v180
	v_mul_f32_e32 v34, v34, v180
	v_mul_f32_e32 v241, v241, v180
	v_mul_f32_e32 v35, v35, v180
	v_mul_f32_e32 v242, v242, v180
	v_mul_f32_e32 v36, v36, v180
	v_mul_f32_e32 v243, v243, v180
	v_mul_f32_e32 v37, v37, v180
	v_mul_f32_e32 v244, v244, v180
	v_mul_f32_e32 v38, v38, v180
	v_mul_f32_e32 v245, v245, v180
	v_mul_f32_e32 v39, v39, v180
	v_fma_f32 v238, v238, v104, v134
	v_fma_f32 v32, v32, v105, v135
	v_fma_f32 v239, v239, v106, v136
	v_fma_f32 v33, v33, v107, v137
	v_fma_f32 v240, v240, v108, v138
	v_fma_f32 v34, v34, v109, v139
	v_fma_f32 v241, v241, v110, v140
	v_fma_f32 v35, v35, v111, v141
	v_fma_f32 v242, v242, v112, v142
	v_fma_f32 v36, v36, v113, v143
	v_fma_f32 v243, v243, v114, v144
	v_fma_f32 v37, v37, v115, v145
	v_fma_f32 v244, v244, v116, v146
	v_fma_f32 v38, v38, v117, v147
	v_fma_f32 v245, v245, v118, v148
	v_fma_f32 v39, v39, v119, v149
	v_cvt_pk_bf16_f32 v150, v238, v32
	v_cvt_pk_bf16_f32 v151, v239, v33
	global_store_dwordx2 v0, v[150:151], s[8:9] offset:0
	v_cvt_pk_bf16_f32 v152, v240, v34
	v_cvt_pk_bf16_f32 v153, v241, v35
	global_store_dwordx2 v0, v[152:153], s[8:9] offset:512
	v_cvt_pk_bf16_f32 v154, v242, v36
	v_cvt_pk_bf16_f32 v155, v243, v37
	global_store_dwordx2 v0, v[154:155], s[8:9] offset:1024
	v_cvt_pk_bf16_f32 v156, v244, v38
	v_cvt_pk_bf16_f32 v157, v245, v39
	global_store_dwordx2 v0, v[156:157], s[8:9] offset:1536
	s_waitcnt vmcnt(36)
	v_lshlrev_b32_e32 v246, 16, v40
	v_and_b32_e32 v40, 0xffff0000, v40
	v_lshlrev_b32_e32 v247, 16, v41
	v_and_b32_e32 v41, 0xffff0000, v41
	v_lshlrev_b32_e32 v248, 16, v42
	v_and_b32_e32 v42, 0xffff0000, v42
	v_lshlrev_b32_e32 v249, 16, v43
	v_and_b32_e32 v43, 0xffff0000, v43
	v_lshlrev_b32_e32 v250, 16, v44
	v_and_b32_e32 v44, 0xffff0000, v44
	v_lshlrev_b32_e32 v251, 16, v45
	v_and_b32_e32 v45, 0xffff0000, v45
	v_lshlrev_b32_e32 v176, 16, v46
	v_and_b32_e32 v46, 0xffff0000, v46
	v_lshlrev_b32_e32 v177, 16, v47
	v_and_b32_e32 v47, 0xffff0000, v47
	v_mul_f32_e32 v178, v246, v246
	v_fmac_f32_e32 v178, v40, v40
	v_fmac_f32_e32 v178, v247, v247
	v_fmac_f32_e32 v178, v41, v41
	v_fmac_f32_e32 v178, v248, v248
	v_fmac_f32_e32 v178, v42, v42
	v_fmac_f32_e32 v178, v249, v249
	v_fmac_f32_e32 v178, v43, v43
	v_fmac_f32_e32 v178, v250, v250
	v_fmac_f32_e32 v178, v44, v44
	v_fmac_f32_e32 v178, v251, v251
	v_fmac_f32_e32 v178, v45, v45
	v_fmac_f32_e32 v178, v176, v176
	v_fmac_f32_e32 v178, v46, v46
	v_fmac_f32_e32 v178, v177, v177
	v_fmac_f32_e32 v178, v47, v47
	s_waitcnt vmcnt(32)
	v_lshlrev_b32_e32 v238, 16, v48
	v_and_b32_e32 v48, 0xffff0000, v48
	v_add_f32_dpp v178, v178, v178 quad_perm:[1,0,3,2] row_mask:0xf bank_mask:0xf bound_ctrl:1
	v_lshlrev_b32_e32 v239, 16, v49
	v_and_b32_e32 v49, 0xffff0000, v49
	v_add_f32_dpp v178, v178, v178 quad_perm:[2,3,0,1] row_mask:0xf bank_mask:0xf bound_ctrl:1
	v_lshlrev_b32_e32 v240, 16, v50
	v_and_b32_e32 v50, 0xffff0000, v50
	v_add_f32_dpp v178, v178, v178 row_half_mirror row_mask:0xf bank_mask:0xf bound_ctrl:1
	v_lshlrev_b32_e32 v241, 16, v51
	v_and_b32_e32 v51, 0xffff0000, v51
	v_add_f32_dpp v178, v178, v178 row_mirror row_mask:0xf bank_mask:0xf bound_ctrl:1
	v_lshlrev_b32_e32 v242, 16, v52
	v_and_b32_e32 v52, 0xffff0000, v52
	v_add_f32_dpp v178, v178, v178 row_bcast:15 row_mask:0xa bank_mask:0xf
	v_lshlrev_b32_e32 v243, 16, v53
	v_and_b32_e32 v53, 0xffff0000, v53
	v_add_f32_dpp v178, v178, v178 row_bcast:31 row_mask:0xc bank_mask:0xf
	v_lshlrev_b32_e32 v244, 16, v54
	v_and_b32_e32 v54, 0xffff0000, v54
	v_lshlrev_b32_e32 v245, 16, v55
	v_and_b32_e32 v55, 0xffff0000, v55
	v_readlane_b32 s0, v178, 63
	s_nop 1
	v_mov_b32_e32 v181, s0
	v_fmamk_f32 v181, v181, 0x3a800000, v161
	v_rsq_f32_e32 v179, v181
	s_nop 0
	v_mul_f32_e32 v246, v246, v179
	v_mul_f32_e32 v40, v40, v179
	v_mul_f32_e32 v247, v247, v179
	v_mul_f32_e32 v41, v41, v179
	v_mul_f32_e32 v248, v248, v179
	v_mul_f32_e32 v42, v42, v179
	v_mul_f32_e32 v249, v249, v179
	v_mul_f32_e32 v43, v43, v179
	v_mul_f32_e32 v250, v250, v179
	v_mul_f32_e32 v44, v44, v179
	v_mul_f32_e32 v251, v251, v179
	v_mul_f32_e32 v45, v45, v179
	v_mul_f32_e32 v176, v176, v179
	v_mul_f32_e32 v46, v46, v179
	v_mul_f32_e32 v177, v177, v179
	v_mul_f32_e32 v47, v47, v179
	v_fmac_f32_e32 v238, v88, v246
	v_fmac_f32_e32 v48, v89, v40
	v_fmac_f32_e32 v239, v90, v247
	v_fmac_f32_e32 v49, v91, v41
	v_fmac_f32_e32 v240, v92, v248
	v_fmac_f32_e32 v50, v93, v42
	v_fmac_f32_e32 v241, v94, v249
	v_fmac_f32_e32 v51, v95, v43
	v_fmac_f32_e32 v242, v96, v250
	v_fmac_f32_e32 v52, v97, v44
	v_fmac_f32_e32 v243, v98, v251
	v_fmac_f32_e32 v53, v99, v45
	v_fmac_f32_e32 v244, v100, v176
	v_fmac_f32_e32 v54, v101, v46
	v_fmac_f32_e32 v245, v102, v177
	v_fmac_f32_e32 v55, v103, v47
	v_cvt_pk_bf16_f32 v120, v238, v48
	v_cvt_pk_bf16_f32 v121, v239, v49
	global_store_dwordx2 v2, v[120:121], s[4:5] offset:0 nt
	v_cvt_pk_bf16_f32 v122, v240, v50
	v_cvt_pk_bf16_f32 v123, v241, v51
	global_store_dwordx2 v2, v[122:123], s[4:5] offset:512 nt
	v_cvt_pk_bf16_f32 v124, v242, v52
	v_cvt_pk_bf16_f32 v125, v243, v53
	global_store_dwordx2 v2, v[124:125], s[4:5] offset:1024 nt
	v_cvt_pk_bf16_f32 v126, v244, v54
	v_cvt_pk_bf16_f32 v127, v245, v55
	global_store_dwordx2 v2, v[126:127], s[4:5] offset:1536 nt
	v_mul_f32_e32 v178, v238, v238
	v_fmac_f32_e32 v178, v48, v48
	v_fmac_f32_e32 v178, v239, v239
	v_fmac_f32_e32 v178, v49, v49
	v_fmac_f32_e32 v178, v240, v240
	v_fmac_f32_e32 v178, v50, v50
	v_fmac_f32_e32 v178, v241, v241
	v_fmac_f32_e32 v178, v51, v51
	v_fmac_f32_e32 v178, v242, v242
	v_fmac_f32_e32 v178, v52, v52
	v_fmac_f32_e32 v178, v243, v243
	v_fmac_f32_e32 v178, v53, v53
	v_fmac_f32_e32 v178, v244, v244
	v_fmac_f32_e32 v178, v54, v54
	v_fmac_f32_e32 v178, v245, v245
	v_fmac_f32_e32 v178, v55, v55
	s_nop 1
	v_add_f32_dpp v178, v178, v178 quad_perm:[1,0,3,2] row_mask:0xf bank_mask:0xf bound_ctrl:1
	s_nop 1
	v_add_f32_dpp v178, v178, v178 quad_perm:[2,3,0,1] row_mask:0xf bank_mask:0xf bound_ctrl:1
	s_nop 1
	v_add_f32_dpp v178, v178, v178 row_half_mirror row_mask:0xf bank_mask:0xf bound_ctrl:1
	s_nop 1
	v_add_f32_dpp v178, v178, v178 row_mirror row_mask:0xf bank_mask:0xf bound_ctrl:1
	s_nop 1
	v_add_f32_dpp v178, v178, v178 row_bcast:15 row_mask:0xa bank_mask:0xf
	s_nop 1
	v_add_f32_dpp v178, v178, v178 row_bcast:31 row_mask:0xc bank_mask:0xf
	s_nop 0
	v_readlane_b32 s0, v178, 63
	s_nop 1
	v_mov_b32_e32 v181, s0
	v_fmamk_f32 v181, v181, 0x3a800000, v161
	v_rsq_f32_e32 v180, v181
	s_nop 0
	v_mul_f32_e32 v238, v238, v180
	v_mul_f32_e32 v48, v48, v180
	v_mul_f32_e32 v239, v239, v180
	v_mul_f32_e32 v49, v49, v180
	v_mul_f32_e32 v240, v240, v180
	v_mul_f32_e32 v50, v50, v180
	v_mul_f32_e32 v241, v241, v180
	v_mul_f32_e32 v51, v51, v180
	v_mul_f32_e32 v242, v242, v180
	v_mul_f32_e32 v52, v52, v180
	v_mul_f32_e32 v243, v243, v180
	v_mul_f32_e32 v53, v53, v180
	v_mul_f32_e32 v244, v244, v180
	v_mul_f32_e32 v54, v54, v180
	v_mul_f32_e32 v245, v245, v180
	v_mul_f32_e32 v55, v55, v180
	v_fma_f32 v238, v238, v104, v134
	v_fma_f32 v48, v48, v105, v135
	v_fma_f32 v239, v239, v106, v136
	v_fma_f32 v49, v49, v107, v137
	v_fma_f32 v240, v240, v108, v138
	v_fma_f32 v50, v50, v109, v139
	v_fma_f32 v241, v241, v110, v140
	v_fma_f32 v51, v51, v111, v141
	v_fma_f32 v242, v242, v112, v142
	v_fma_f32 v52, v52, v113, v143
	v_fma_f32 v243, v243, v114, v144
	v_fma_f32 v53, v53, v115, v145
	v_fma_f32 v244, v244, v116, v146
	v_fma_f32 v54, v54, v117, v147
	v_fma_f32 v245, v245, v118, v148
	v_fma_f32 v55, v55, v119, v149
	v_cvt_pk_bf16_f32 v150, v238, v48
	v_cvt_pk_bf16_f32 v151, v239, v49
	global_store_dwordx2 v2, v[150:151], s[8:9] offset:0
	v_cvt_pk_bf16_f32 v152, v240, v50
	v_cvt_pk_bf16_f32 v153, v241, v51
	global_store_dwordx2 v2, v[152:153], s[8:9] offset:512
	v_cvt_pk_bf16_f32 v154, v242, v52
	v_cvt_pk_bf16_f32 v155, v243, v53
	global_store_dwordx2 v2, v[154:155], s[8:9] offset:1024
	v_cvt_pk_bf16_f32 v156, v244, v54
	v_cvt_pk_bf16_f32 v157, v245, v55
	global_store_dwordx2 v2, v[156:157], s[8:9] offset:1536
	s_waitcnt vmcnt(28)
	v_lshlrev_b32_e32 v246, 16, v8
	v_and_b32_e32 v8, 0xffff0000, v8
	v_lshlrev_b32_e32 v247, 16, v9
	v_and_b32_e32 v9, 0xffff0000, v9
	v_lshlrev_b32_e32 v248, 16, v10
	v_and_b32_e32 v10, 0xffff0000, v10
	v_lshlrev_b32_e32 v249, 16, v11
	v_and_b32_e32 v11, 0xffff0000, v11
	v_lshlrev_b32_e32 v250, 16, v12
	v_and_b32_e32 v12, 0xffff0000, v12
	v_lshlrev_b32_e32 v251, 16, v13
	v_and_b32_e32 v13, 0xffff0000, v13
	v_lshlrev_b32_e32 v176, 16, v14
	v_and_b32_e32 v14, 0xffff0000, v14
	v_lshlrev_b32_e32 v177, 16, v15
	v_and_b32_e32 v15, 0xffff0000, v15
	v_mul_f32_e32 v178, v246, v246
	v_fmac_f32_e32 v178, v8, v8
	v_fmac_f32_e32 v178, v247, v247
	v_fmac_f32_e32 v178, v9, v9
	v_fmac_f32_e32 v178, v248, v248
	v_fmac_f32_e32 v178, v10, v10
	v_fmac_f32_e32 v178, v249, v249
	v_fmac_f32_e32 v178, v11, v11
	v_fmac_f32_e32 v178, v250, v250
	v_fmac_f32_e32 v178, v12, v12
	v_fmac_f32_e32 v178, v251, v251
	v_fmac_f32_e32 v178, v13, v13
	v_fmac_f32_e32 v178, v176, v176
	v_fmac_f32_e32 v178, v14, v14
	v_fmac_f32_e32 v178, v177, v177
	v_fmac_f32_e32 v178, v15, v15
	s_waitcnt vmcnt(24)
	v_lshlrev_b32_e32 v238, 16, v16
	v_and_b32_e32 v16, 0xffff0000, v16
	v_add_f32_dpp v178, v178, v178 quad_perm:[1,0,3,2] row_mask:0xf bank_mask:0xf bound_ctrl:1
	v_lshlrev_b32_e32 v239, 16, v17
	v_and_b32_e32 v17, 0xffff0000, v17
	v_add_f32_dpp v178, v178, v178 quad_perm:[2,3,0,1] row_mask:0xf bank_mask:0xf bound_ctrl:1
	v_lshlrev_b32_e32 v240, 16, v18
	v_and_b32_e32 v18, 0xffff0000, v18
	v_add_f32_dpp v178, v178, v178 row_half_mirror row_mask:0xf bank_mask:0xf bound_ctrl:1
	v_lshlrev_b32_e32 v241, 16, v19
	v_and_b32_e32 v19, 0xffff0000, v19
	v_add_f32_dpp v178, v178, v178 row_mirror row_mask:0xf bank_mask:0xf bound_ctrl:1
	v_lshlrev_b32_e32 v242, 16, v20
	v_and_b32_e32 v20, 0xffff0000, v20
	v_add_f32_dpp v178, v178, v178 row_bcast:15 row_mask:0xa bank_mask:0xf
	v_lshlrev_b32_e32 v243, 16, v21
	v_and_b32_e32 v21, 0xffff0000, v21
	v_add_f32_dpp v178, v178, v178 row_bcast:31 row_mask:0xc bank_mask:0xf
	v_lshlrev_b32_e32 v244, 16, v22
	v_and_b32_e32 v22, 0xffff0000, v22
	v_lshlrev_b32_e32 v245, 16, v23
	v_and_b32_e32 v23, 0xffff0000, v23
	v_readlane_b32 s0, v178, 63
	s_nop 1
	v_mov_b32_e32 v181, s0
	v_fmamk_f32 v181, v181, 0x3a800000, v161
	v_rsq_f32_e32 v179, v181
	s_nop 0
	v_mul_f32_e32 v246, v246, v179
	v_mul_f32_e32 v8, v8, v179
	v_mul_f32_e32 v247, v247, v179
	v_mul_f32_e32 v9, v9, v179
	v_mul_f32_e32 v248, v248, v179
	v_mul_f32_e32 v10, v10, v179
	v_mul_f32_e32 v249, v249, v179
	v_mul_f32_e32 v11, v11, v179
	v_mul_f32_e32 v250, v250, v179
	v_mul_f32_e32 v12, v12, v179
	v_mul_f32_e32 v251, v251, v179
	v_mul_f32_e32 v13, v13, v179
	v_mul_f32_e32 v176, v176, v179
	v_mul_f32_e32 v14, v14, v179
	v_mul_f32_e32 v177, v177, v179
	v_mul_f32_e32 v15, v15, v179
	v_fmac_f32_e32 v238, v88, v246
	v_fmac_f32_e32 v16, v89, v8
	v_fmac_f32_e32 v239, v90, v247
	v_fmac_f32_e32 v17, v91, v9
	v_fmac_f32_e32 v240, v92, v248
	v_fmac_f32_e32 v18, v93, v10
	v_fmac_f32_e32 v241, v94, v249
	v_fmac_f32_e32 v19, v95, v11
	v_fmac_f32_e32 v242, v96, v250
	v_fmac_f32_e32 v20, v97, v12
	v_fmac_f32_e32 v243, v98, v251
	v_fmac_f32_e32 v21, v99, v13
	v_fmac_f32_e32 v244, v100, v176
	v_fmac_f32_e32 v22, v101, v14
	v_fmac_f32_e32 v245, v102, v177
	v_fmac_f32_e32 v23, v103, v15
	v_cvt_pk_bf16_f32 v120, v238, v16
	v_cvt_pk_bf16_f32 v121, v239, v17
	global_store_dwordx2 v3, v[120:121], s[4:5] offset:0 nt
	v_cvt_pk_bf16_f32 v122, v240, v18
	v_cvt_pk_bf16_f32 v123, v241, v19
	global_store_dwordx2 v3, v[122:123], s[4:5] offset:512 nt
	v_cvt_pk_bf16_f32 v124, v242, v20
	v_cvt_pk_bf16_f32 v125, v243, v21
	global_store_dwordx2 v3, v[124:125], s[4:5] offset:1024 nt
	v_cvt_pk_bf16_f32 v126, v244, v22
	v_cvt_pk_bf16_f32 v127, v245, v23
	global_store_dwordx2 v3, v[126:127], s[4:5] offset:1536 nt
	v_mul_f32_e32 v178, v238, v238
	v_fmac_f32_e32 v178, v16, v16
	v_fmac_f32_e32 v178, v239, v239
	v_fmac_f32_e32 v178, v17, v17
	v_fmac_f32_e32 v178, v240, v240
	v_fmac_f32_e32 v178, v18, v18
	v_fmac_f32_e32 v178, v241, v241
	v_fmac_f32_e32 v178, v19, v19
	v_fmac_f32_e32 v178, v242, v242
	v_fmac_f32_e32 v178, v20, v20
	v_fmac_f32_e32 v178, v243, v243
	v_fmac_f32_e32 v178, v21, v21
	v_fmac_f32_e32 v178, v244, v244
	v_fmac_f32_e32 v178, v22, v22
	v_fmac_f32_e32 v178, v245, v245
	v_fmac_f32_e32 v178, v23, v23
	s_nop 1
	v_add_f32_dpp v178, v178, v178 quad_perm:[1,0,3,2] row_mask:0xf bank_mask:0xf bound_ctrl:1
	s_nop 1
	v_add_f32_dpp v178, v178, v178 quad_perm:[2,3,0,1] row_mask:0xf bank_mask:0xf bound_ctrl:1
	s_nop 1
	v_add_f32_dpp v178, v178, v178 row_half_mirror row_mask:0xf bank_mask:0xf bound_ctrl:1
	s_nop 1
	v_add_f32_dpp v178, v178, v178 row_mirror row_mask:0xf bank_mask:0xf bound_ctrl:1
	s_nop 1
	v_add_f32_dpp v178, v178, v178 row_bcast:15 row_mask:0xa bank_mask:0xf
	s_nop 1
	v_add_f32_dpp v178, v178, v178 row_bcast:31 row_mask:0xc bank_mask:0xf
	s_nop 0
	v_readlane_b32 s0, v178, 63
	s_nop 1
	v_mov_b32_e32 v181, s0
	v_fmamk_f32 v181, v181, 0x3a800000, v161
	v_rsq_f32_e32 v180, v181
	s_nop 0
	v_mul_f32_e32 v238, v238, v180
	v_mul_f32_e32 v16, v16, v180
	v_mul_f32_e32 v239, v239, v180
	v_mul_f32_e32 v17, v17, v180
	v_mul_f32_e32 v240, v240, v180
	v_mul_f32_e32 v18, v18, v180
	v_mul_f32_e32 v241, v241, v180
	v_mul_f32_e32 v19, v19, v180
	v_mul_f32_e32 v242, v242, v180
	v_mul_f32_e32 v20, v20, v180
	v_mul_f32_e32 v243, v243, v180
	v_mul_f32_e32 v21, v21, v180
	v_mul_f32_e32 v244, v244, v180
	v_mul_f32_e32 v22, v22, v180
	v_mul_f32_e32 v245, v245, v180
	v_mul_f32_e32 v23, v23, v180
	v_fma_f32 v238, v238, v104, v134
	v_fma_f32 v16, v16, v105, v135
	v_fma_f32 v239, v239, v106, v136
	v_fma_f32 v17, v17, v107, v137
	v_fma_f32 v240, v240, v108, v138
	v_fma_f32 v18, v18, v109, v139
	v_fma_f32 v241, v241, v110, v140
	v_fma_f32 v19, v19, v111, v141
	v_fma_f32 v242, v242, v112, v142
	v_fma_f32 v20, v20, v113, v143
	v_fma_f32 v243, v243, v114, v144
	v_fma_f32 v21, v21, v115, v145
	v_fma_f32 v244, v244, v116, v146
	v_fma_f32 v22, v22, v117, v147
	v_fma_f32 v245, v245, v118, v148
	v_fma_f32 v23, v23, v119, v149
	v_cvt_pk_bf16_f32 v150, v238, v16
	v_cvt_pk_bf16_f32 v151, v239, v17
	global_store_dwordx2 v3, v[150:151], s[8:9] offset:0
	v_cvt_pk_bf16_f32 v152, v240, v18
	v_cvt_pk_bf16_f32 v153, v241, v19
	global_store_dwordx2 v3, v[152:153], s[8:9] offset:512
	v_cvt_pk_bf16_f32 v154, v242, v20
	v_cvt_pk_bf16_f32 v155, v243, v21
	global_store_dwordx2 v3, v[154:155], s[8:9] offset:1024
	v_cvt_pk_bf16_f32 v156, v244, v22
	v_cvt_pk_bf16_f32 v157, v245, v23
	global_store_dwordx2 v3, v[156:157], s[8:9] offset:1536
	s_waitcnt vmcnt(28)
	v_lshlrev_b32_e32 v246, 16, v190
	v_and_b32_e32 v190, 0xffff0000, v190
	v_lshlrev_b32_e32 v247, 16, v191
	v_and_b32_e32 v191, 0xffff0000, v191
	v_lshlrev_b32_e32 v248, 16, v192
	v_and_b32_e32 v192, 0xffff0000, v192
	v_lshlrev_b32_e32 v249, 16, v193
	v_and_b32_e32 v193, 0xffff0000, v193
	v_lshlrev_b32_e32 v250, 16, v194
	v_and_b32_e32 v194, 0xffff0000, v194
	v_lshlrev_b32_e32 v251, 16, v195
	v_and_b32_e32 v195, 0xffff0000, v195
	v_lshlrev_b32_e32 v176, 16, v196
	v_and_b32_e32 v196, 0xffff0000, v196
	v_lshlrev_b32_e32 v177, 16, v197
	v_and_b32_e32 v197, 0xffff0000, v197
	v_mul_f32_e32 v178, v246, v246
	v_fmac_f32_e32 v178, v190, v190
	v_fmac_f32_e32 v178, v247, v247
	v_fmac_f32_e32 v178, v191, v191
	v_fmac_f32_e32 v178, v248, v248
	v_fmac_f32_e32 v178, v192, v192
	v_fmac_f32_e32 v178, v249, v249
	v_fmac_f32_e32 v178, v193, v193
	v_fmac_f32_e32 v178, v250, v250
	v_fmac_f32_e32 v178, v194, v194
	v_fmac_f32_e32 v178, v251, v251
	v_fmac_f32_e32 v178, v195, v195
	v_fmac_f32_e32 v178, v176, v176
	v_fmac_f32_e32 v178, v196, v196
	v_fmac_f32_e32 v178, v177, v177
	v_fmac_f32_e32 v178, v197, v197
	s_waitcnt vmcnt(24)
	v_lshlrev_b32_e32 v238, 16, v198
	v_and_b32_e32 v198, 0xffff0000, v198
	v_add_f32_dpp v178, v178, v178 quad_perm:[1,0,3,2] row_mask:0xf bank_mask:0xf bound_ctrl:1
	v_lshlrev_b32_e32 v239, 16, v199
	v_and_b32_e32 v199, 0xffff0000, v199
	v_add_f32_dpp v178, v178, v178 quad_perm:[2,3,0,1] row_mask:0xf bank_mask:0xf bound_ctrl:1
	v_lshlrev_b32_e32 v240, 16, v200
	v_and_b32_e32 v200, 0xffff0000, v200
	v_add_f32_dpp v178, v178, v178 row_half_mirror row_mask:0xf bank_mask:0xf bound_ctrl:1
	v_lshlrev_b32_e32 v241, 16, v201
	v_and_b32_e32 v201, 0xffff0000, v201
	v_add_f32_dpp v178, v178, v178 row_mirror row_mask:0xf bank_mask:0xf bound_ctrl:1
	v_lshlrev_b32_e32 v242, 16, v202
	v_and_b32_e32 v202, 0xffff0000, v202
	v_add_f32_dpp v178, v178, v178 row_bcast:15 row_mask:0xa bank_mask:0xf
	v_lshlrev_b32_e32 v243, 16, v203
	v_and_b32_e32 v203, 0xffff0000, v203
	v_add_f32_dpp v178, v178, v178 row_bcast:31 row_mask:0xc bank_mask:0xf
	v_lshlrev_b32_e32 v244, 16, v204
	v_and_b32_e32 v204, 0xffff0000, v204
	v_lshlrev_b32_e32 v245, 16, v205
	v_and_b32_e32 v205, 0xffff0000, v205
	v_readlane_b32 s0, v178, 63
	s_nop 1
	v_mov_b32_e32 v181, s0
	v_fmamk_f32 v181, v181, 0x3a800000, v161
	v_rsq_f32_e32 v179, v181
	s_nop 0
	v_mul_f32_e32 v246, v246, v179
	v_mul_f32_e32 v190, v190, v179
	v_mul_f32_e32 v247, v247, v179
	v_mul_f32_e32 v191, v191, v179
	v_mul_f32_e32 v248, v248, v179
	v_mul_f32_e32 v192, v192, v179
	v_mul_f32_e32 v249, v249, v179
	v_mul_f32_e32 v193, v193, v179
	v_mul_f32_e32 v250, v250, v179
	v_mul_f32_e32 v194, v194, v179
	v_mul_f32_e32 v251, v251, v179
	v_mul_f32_e32 v195, v195, v179
	v_mul_f32_e32 v176, v176, v179
	v_mul_f32_e32 v196, v196, v179
	v_mul_f32_e32 v177, v177, v179
	v_mul_f32_e32 v197, v197, v179
	v_fmac_f32_e32 v238, v88, v246
	v_fmac_f32_e32 v198, v89, v190
	v_fmac_f32_e32 v239, v90, v247
	v_fmac_f32_e32 v199, v91, v191
	v_fmac_f32_e32 v240, v92, v248
	v_fmac_f32_e32 v200, v93, v192
	v_fmac_f32_e32 v241, v94, v249
	v_fmac_f32_e32 v201, v95, v193
	v_fmac_f32_e32 v242, v96, v250
	v_fmac_f32_e32 v202, v97, v194
	v_fmac_f32_e32 v243, v98, v251
	v_fmac_f32_e32 v203, v99, v195
	v_fmac_f32_e32 v244, v100, v176
	v_fmac_f32_e32 v204, v101, v196
	v_fmac_f32_e32 v245, v102, v177
	v_fmac_f32_e32 v205, v103, v197
	v_cvt_pk_bf16_f32 v120, v238, v198
	v_cvt_pk_bf16_f32 v121, v239, v199
	global_store_dwordx2 v4, v[120:121], s[4:5] offset:0 nt
	v_cvt_pk_bf16_f32 v122, v240, v200
	v_cvt_pk_bf16_f32 v123, v241, v201
	global_store_dwordx2 v4, v[122:123], s[4:5] offset:512 nt
	v_cvt_pk_bf16_f32 v124, v242, v202
	v_cvt_pk_bf16_f32 v125, v243, v203
	global_store_dwordx2 v4, v[124:125], s[4:5] offset:1024 nt
	v_cvt_pk_bf16_f32 v126, v244, v204
	v_cvt_pk_bf16_f32 v127, v245, v205
	global_store_dwordx2 v4, v[126:127], s[4:5] offset:1536 nt
	v_mul_f32_e32 v178, v238, v238
	v_fmac_f32_e32 v178, v198, v198
	v_fmac_f32_e32 v178, v239, v239
	v_fmac_f32_e32 v178, v199, v199
	v_fmac_f32_e32 v178, v240, v240
	v_fmac_f32_e32 v178, v200, v200
	v_fmac_f32_e32 v178, v241, v241
	v_fmac_f32_e32 v178, v201, v201
	v_fmac_f32_e32 v178, v242, v242
	v_fmac_f32_e32 v178, v202, v202
	v_fmac_f32_e32 v178, v243, v243
	v_fmac_f32_e32 v178, v203, v203
	v_fmac_f32_e32 v178, v244, v244
	v_fmac_f32_e32 v178, v204, v204
	v_fmac_f32_e32 v178, v245, v245
	v_fmac_f32_e32 v178, v205, v205
	s_nop 1
	v_add_f32_dpp v178, v178, v178 quad_perm:[1,0,3,2] row_mask:0xf bank_mask:0xf bound_ctrl:1
	s_nop 1
	v_add_f32_dpp v178, v178, v178 quad_perm:[2,3,0,1] row_mask:0xf bank_mask:0xf bound_ctrl:1
	s_nop 1
	v_add_f32_dpp v178, v178, v178 row_half_mirror row_mask:0xf bank_mask:0xf bound_ctrl:1
	s_nop 1
	v_add_f32_dpp v178, v178, v178 row_mirror row_mask:0xf bank_mask:0xf bound_ctrl:1
	s_nop 1
	v_add_f32_dpp v178, v178, v178 row_bcast:15 row_mask:0xa bank_mask:0xf
	s_nop 1
	v_add_f32_dpp v178, v178, v178 row_bcast:31 row_mask:0xc bank_mask:0xf
	s_nop 0
	v_readlane_b32 s0, v178, 63
	s_nop 1
	v_mov_b32_e32 v181, s0
	v_fmamk_f32 v181, v181, 0x3a800000, v161
	v_rsq_f32_e32 v180, v181
	s_nop 0
	v_mul_f32_e32 v238, v238, v180
	v_mul_f32_e32 v198, v198, v180
	v_mul_f32_e32 v239, v239, v180
	v_mul_f32_e32 v199, v199, v180
	v_mul_f32_e32 v240, v240, v180
	v_mul_f32_e32 v200, v200, v180
	v_mul_f32_e32 v241, v241, v180
	v_mul_f32_e32 v201, v201, v180
	v_mul_f32_e32 v242, v242, v180
	v_mul_f32_e32 v202, v202, v180
	v_mul_f32_e32 v243, v243, v180
	v_mul_f32_e32 v203, v203, v180
	v_mul_f32_e32 v244, v244, v180
	v_mul_f32_e32 v204, v204, v180
	v_mul_f32_e32 v245, v245, v180
	v_mul_f32_e32 v205, v205, v180
	v_fma_f32 v238, v238, v104, v134
	v_fma_f32 v198, v198, v105, v135
	v_fma_f32 v239, v239, v106, v136
	v_fma_f32 v199, v199, v107, v137
	v_fma_f32 v240, v240, v108, v138
	v_fma_f32 v200, v200, v109, v139
	v_fma_f32 v241, v241, v110, v140
	v_fma_f32 v201, v201, v111, v141
	v_fma_f32 v242, v242, v112, v142
	v_fma_f32 v202, v202, v113, v143
	v_fma_f32 v243, v243, v114, v144
	v_fma_f32 v203, v203, v115, v145
	v_fma_f32 v244, v244, v116, v146
	v_fma_f32 v204, v204, v117, v147
	v_fma_f32 v245, v245, v118, v148
	v_fma_f32 v205, v205, v119, v149
	v_cvt_pk_bf16_f32 v150, v238, v198
	v_cvt_pk_bf16_f32 v151, v239, v199
	global_store_dwordx2 v4, v[150:151], s[8:9] offset:0
	v_cvt_pk_bf16_f32 v152, v240, v200
	v_cvt_pk_bf16_f32 v153, v241, v201
	global_store_dwordx2 v4, v[152:153], s[8:9] offset:512
	v_cvt_pk_bf16_f32 v154, v242, v202
	v_cvt_pk_bf16_f32 v155, v243, v203
	global_store_dwordx2 v4, v[154:155], s[8:9] offset:1024
	v_cvt_pk_bf16_f32 v156, v244, v204
	v_cvt_pk_bf16_f32 v157, v245, v205
	global_store_dwordx2 v4, v[156:157], s[8:9] offset:1536
	s_mov_b64 s[0:1], 0
	s_branch .LBB0_190
